# v26 + write-through non-temporal (sc1 nt) stores for the in-proj Z output and the norm-pass x / final output
# speedup vs baseline: 1.0299x; 1.0024x over previous
.LBB0_145:
	v_pk_mul_f32 v[174:175], v[126:127], v[164:165]
	v_lshl_or_b32 v158, s55, 8, v168
	v_sub_f32_e32 v0, v174, v175
	v_mov_b32_e32 v174, v165
	v_mov_b32_e32 v175, v164
	v_pk_mul_f32 v[126:127], v[126:127], v[174:175]
	v_mov_b64_e32 v[172:173], s[12:13]
	v_add_f32_e32 v171, v126, v127
	v_pk_mul_f32 v[126:127], v[128:129], v[130:131]
	v_mov_b32_e32 v176, v133
	v_sub_f32_e32 v178, v126, v127
	v_mov_b32_e32 v126, v131
	v_mov_b32_e32 v127, v130
	v_pk_mul_f32 v[128:129], v[128:129], v[126:127]
	v_mov_b32_e32 v177, v132
	v_add_f32_e32 v179, v128, v129
	v_pk_mul_f32 v[128:129], v[122:123], v[162:163]
	v_ashrrev_i32_e32 v159, 31, v158
	v_sub_f32_e32 v180, v128, v129
	v_mov_b32_e32 v128, v163
	v_mov_b32_e32 v129, v162
	v_pk_mul_f32 v[122:123], v[122:123], v[128:129]
	v_mad_i64_i32 v[172:173], s[0:1], v170, s43, v[172:173]
	v_add_f32_e32 v181, v122, v123
	v_pk_mul_f32 v[122:123], v[124:125], v[132:133]
	v_lshl_add_u64 v[172:173], v[158:159], 1, v[172:173]
	v_sub_f32_e32 v182, v122, v123
	v_pk_mul_f32 v[122:123], v[124:125], v[176:177]
	s_nop 0
	v_add_f32_e32 v125, v122, v123
	v_cvt_pk_bf16_f32 v122, v0, v171
	v_cvt_pk_bf16_f32 v123, v178, v179
	v_cvt_pk_bf16_f32 v124, v180, v181
	v_cvt_pk_bf16_f32 v125, v182, v125
	global_store_dwordx4 v[172:173], v[122:125], off sc1 nt
	s_nop 1
	v_pk_mul_f32 v[122:123], v[118:119], v[164:165]
	v_pk_mul_f32 v[118:119], v[118:119], v[174:175]
	v_sub_f32_e32 v0, v122, v123
	v_add_f32_e32 v122, v118, v119
	v_pk_mul_f32 v[118:119], v[120:121], v[130:131]
	s_nop 0
	v_sub_f32_e32 v123, v118, v119
	v_pk_mul_f32 v[118:119], v[120:121], v[126:127]
	s_nop 0
	v_add_f32_e32 v120, v118, v119
	v_pk_mul_f32 v[118:119], v[114:115], v[162:163]
	v_pk_mul_f32 v[114:115], v[114:115], v[128:129]
	v_sub_f32_e32 v118, v118, v119
	v_add_f32_e32 v119, v114, v115
	v_pk_mul_f32 v[114:115], v[116:117], v[132:133]
	s_nop 0
	v_sub_f32_e32 v121, v114, v115
	v_pk_mul_f32 v[114:115], v[116:117], v[176:177]
	s_nop 0
	v_add_f32_e32 v117, v114, v115
	v_cvt_pk_bf16_f32 v114, v0, v122
	v_cvt_pk_bf16_f32 v115, v123, v120
	v_cvt_pk_bf16_f32 v116, v118, v119
	v_cvt_pk_bf16_f32 v117, v121, v117
	global_store_dwordx4 v[172:173], v[114:117], off offset:256 sc1 nt
	v_cndmask_b32_e64 v0, 0, 1, s[10:11]
	v_or_b32_e32 v120, 16, v170
	v_cmp_ne_u32_e64 s[8:9], 1, v0
	s_andn2_b64 vcc, exec, s[10:11]
	v_mov_b32_e32 v115, 0
	v_mov_b32_e32 v119, 0
	v_mov_b32_e32 v117, 0
	v_mov_b32_e32 v114, 1.0
	v_mov_b32_e32 v118, 1.0
	v_mov_b32_e32 v116, 1.0
	s_cbranch_vccnz .LBB0_147
	s_waitcnt vmcnt(10)
	v_mov_b32_e32 v114, v192
	v_mov_b32_e32 v115, v193
	v_mov_b32_e32 v116, v194
	v_mov_b32_e32 v117, v195
	v_mov_b32_e32 v122, v196
	v_mov_b32_e32 v123, v197
	v_mov_b32_e32 v124, v198
	v_mov_b32_e32 v125, v199
	v_mov_b32_e32 v161, v114
	v_mov_b32_e32 v119, v116
	v_mov_b32_e32 v160, v122
	v_mov_b32_e32 v114, v123
	v_mov_b32_e32 v118, v124
	v_mov_b32_e32 v116, v125
.LBB0_147:
	v_mov_b64_e32 v[122:123], s[12:13]
	v_mad_i64_i32 v[120:121], s[0:1], v120, s43, v[122:123]
	v_pk_mul_f32 v[122:123], v[110:111], v[160:161]
	v_mov_b32_e32 v124, v117
	v_sub_f32_e32 v0, v122, v123
	v_mov_b32_e32 v122, v161
	v_mov_b32_e32 v123, v160
	v_pk_mul_f32 v[110:111], v[110:111], v[122:123]
	v_mov_b32_e32 v125, v116
	v_add_f32_e32 v126, v110, v111
	v_pk_mul_f32 v[110:111], v[112:113], v[114:115]
	v_lshl_add_u64 v[120:121], v[158:159], 1, v[120:121]
	v_sub_f32_e32 v127, v110, v111
	v_mov_b32_e32 v110, v115
	v_mov_b32_e32 v111, v114
	v_pk_mul_f32 v[112:113], v[112:113], v[110:111]
	s_nop 0
	v_add_f32_e32 v128, v112, v113
	v_pk_mul_f32 v[112:113], v[106:107], v[118:119]
	s_nop 0
	v_sub_f32_e32 v129, v112, v113
	v_mov_b32_e32 v112, v119
	v_mov_b32_e32 v113, v118
	v_pk_mul_f32 v[106:107], v[106:107], v[112:113]
	s_nop 0
	v_add_f32_e32 v130, v106, v107
	v_pk_mul_f32 v[106:107], v[108:109], v[116:117]
	s_nop 0
	v_sub_f32_e32 v131, v106, v107
	v_pk_mul_f32 v[106:107], v[108:109], v[124:125]
	s_nop 0
	v_add_f32_e32 v109, v106, v107
	v_cvt_pk_bf16_f32 v106, v0, v126
	v_cvt_pk_bf16_f32 v107, v127, v128
	v_cvt_pk_bf16_f32 v108, v129, v130
	v_cvt_pk_bf16_f32 v109, v131, v109
	global_store_dwordx4 v[120:121], v[106:109], off sc1 nt
	s_nop 1
	v_pk_mul_f32 v[106:107], v[102:103], v[160:161]
	v_pk_mul_f32 v[102:103], v[102:103], v[122:123]
	v_sub_f32_e32 v0, v106, v107
	v_add_f32_e32 v106, v102, v103
	v_pk_mul_f32 v[102:103], v[104:105], v[114:115]
	s_nop 0
	v_sub_f32_e32 v107, v102, v103
	v_pk_mul_f32 v[102:103], v[104:105], v[110:111]
	s_nop 0
	v_add_f32_e32 v104, v102, v103
	v_pk_mul_f32 v[102:103], v[98:99], v[118:119]
	v_pk_mul_f32 v[98:99], v[98:99], v[112:113]
	v_sub_f32_e32 v102, v102, v103
	v_add_f32_e32 v103, v98, v99
	v_pk_mul_f32 v[98:99], v[100:101], v[116:117]
	s_nop 0
	v_sub_f32_e32 v105, v98, v99
	v_pk_mul_f32 v[98:99], v[100:101], v[124:125]
	s_nop 0
	v_add_f32_e32 v101, v98, v99
	v_cvt_pk_bf16_f32 v98, v0, v106
	v_cvt_pk_bf16_f32 v99, v107, v104
	v_cvt_pk_bf16_f32 v100, v102, v103
	v_cvt_pk_bf16_f32 v101, v105, v101
	global_store_dwordx4 v[120:121], v[98:101], off offset:256 sc1 nt
	v_or_b32_e32 v108, 32, v170
	v_mov_b32_e32 v102, 1.0
	v_mov_b32_e32 v103, 0
	s_and_b64 vcc, exec, s[8:9]
	v_mov_b32_e32 v107, 0
	v_mov_b32_e32 v99, 0
	v_mov_b32_e32 v105, 0
	v_mov_b32_e32 v101, 0
	v_mov_b32_e32 v106, 1.0
	v_mov_b32_e32 v98, 1.0
	v_mov_b32_e32 v104, 1.0
	v_mov_b32_e32 v100, 1.0
	s_cbranch_vccnz .LBB0_149
	v_add_u32_e32 v244, 0xa0, v170
	v_lshlrev_b32_e32 v244, 8, v244
	v_and_b32_e32 v244, 0x7ff00, v244
	v_lshl_add_u64 v[246:247], v[142:143], 0, v[244:245]
	global_load_dwordx4 v[184:187], v[246:247], off
	v_lshl_add_u64 v[246:247], v[144:145], 0, v[244:245]
	global_load_dwordx4 v[188:191], v[246:247], off
	v_add_u32_e32 v244, 0xb0, v170
	v_lshlrev_b32_e32 v244, 8, v244
	v_and_b32_e32 v244, 0x7ff00, v244
	v_lshl_add_u64 v[246:247], v[142:143], 0, v[244:245]
	global_load_dwordx4 v[192:195], v[246:247], off
	v_lshl_add_u64 v[246:247], v[144:145], 0, v[244:245]
	global_load_dwordx4 v[196:199], v[246:247], off
	s_waitcnt vmcnt(14)
	v_mov_b32_e32 v98, v200
	v_mov_b32_e32 v99, v201
	v_mov_b32_e32 v100, v202
	v_mov_b32_e32 v101, v203
	v_mov_b32_e32 v110, v216
	v_mov_b32_e32 v111, v217
	v_mov_b32_e32 v112, v218
	v_mov_b32_e32 v113, v219
	v_mov_b32_e32 v107, v98
	v_mov_b32_e32 v105, v100
	v_mov_b32_e32 v106, v110
	v_mov_b32_e32 v98, v111
	v_mov_b32_e32 v104, v112
	v_mov_b32_e32 v100, v113
.LBB0_149:
	v_mov_b64_e32 v[110:111], s[12:13]
	v_mad_i64_i32 v[108:109], s[0:1], v108, s43, v[110:111]
	v_pk_mul_f32 v[110:111], v[94:95], v[106:107]
	v_mov_b32_e32 v112, v101
	v_sub_f32_e32 v0, v110, v111
	v_mov_b32_e32 v110, v107
	v_mov_b32_e32 v111, v106
	v_pk_mul_f32 v[94:95], v[94:95], v[110:111]
	v_mov_b32_e32 v113, v100
	v_add_f32_e32 v114, v94, v95
	v_pk_mul_f32 v[94:95], v[96:97], v[98:99]
	v_lshl_add_u64 v[108:109], v[158:159], 1, v[108:109]
	v_sub_f32_e32 v115, v94, v95
	v_mov_b32_e32 v94, v99
	v_mov_b32_e32 v95, v98
	v_pk_mul_f32 v[96:97], v[96:97], v[94:95]
	s_nop 0
	v_add_f32_e32 v116, v96, v97
	v_pk_mul_f32 v[96:97], v[90:91], v[104:105]
	s_nop 0
	v_sub_f32_e32 v117, v96, v97
	v_mov_b32_e32 v96, v105
	v_mov_b32_e32 v97, v104
	v_pk_mul_f32 v[90:91], v[90:91], v[96:97]
	s_nop 0
	v_add_f32_e32 v118, v90, v91
	v_pk_mul_f32 v[90:91], v[92:93], v[100:101]
	s_nop 0
	v_sub_f32_e32 v119, v90, v91
	v_pk_mul_f32 v[90:91], v[92:93], v[112:113]
	s_nop 0
	v_add_f32_e32 v93, v90, v91
	v_cvt_pk_bf16_f32 v90, v0, v114
	v_cvt_pk_bf16_f32 v91, v115, v116
	v_cvt_pk_bf16_f32 v92, v117, v118
	v_cvt_pk_bf16_f32 v93, v119, v93
	global_store_dwordx4 v[108:109], v[90:93], off sc1 nt
	s_nop 1
	v_pk_mul_f32 v[90:91], v[86:87], v[106:107]
	v_pk_mul_f32 v[86:87], v[86:87], v[110:111]
	v_sub_f32_e32 v0, v90, v91
	v_add_f32_e32 v90, v86, v87
	v_pk_mul_f32 v[86:87], v[88:89], v[98:99]
	s_nop 0
	v_sub_f32_e32 v91, v86, v87
	v_pk_mul_f32 v[86:87], v[88:89], v[94:95]
	s_nop 0
	v_add_f32_e32 v88, v86, v87
	v_pk_mul_f32 v[86:87], v[82:83], v[104:105]
	v_pk_mul_f32 v[82:83], v[82:83], v[96:97]
	v_sub_f32_e32 v86, v86, v87
	v_add_f32_e32 v87, v82, v83
	v_pk_mul_f32 v[82:83], v[84:85], v[100:101]
	s_nop 0
	v_sub_f32_e32 v89, v82, v83
	v_pk_mul_f32 v[82:83], v[84:85], v[112:113]
	s_nop 0
	v_add_f32_e32 v85, v82, v83
	v_cvt_pk_bf16_f32 v82, v0, v90
	v_cvt_pk_bf16_f32 v83, v91, v88
	v_cvt_pk_bf16_f32 v84, v86, v87
	v_cvt_pk_bf16_f32 v85, v89, v85
	global_store_dwordx4 v[108:109], v[82:85], off offset:256 sc1 nt
	v_or_b32_e32 v88, 48, v170
	s_and_b64 vcc, exec, s[8:9]
	v_mov_b32_e32 v83, 0
	v_mov_b32_e32 v87, 0
	v_mov_b32_e32 v85, 0
	v_mov_b32_e32 v82, 1.0
	v_mov_b32_e32 v86, 1.0
	v_mov_b32_e32 v84, 1.0
	s_cbranch_vccnz .LBB0_151
	s_waitcnt vmcnt(14)
	v_mov_b32_e32 v82, v220
	v_mov_b32_e32 v83, v221
	v_mov_b32_e32 v84, v222
	v_mov_b32_e32 v85, v223
	v_mov_b32_e32 v90, v224
	v_mov_b32_e32 v91, v225
	v_mov_b32_e32 v92, v226
	v_mov_b32_e32 v93, v227
	v_mov_b32_e32 v103, v82
	v_mov_b32_e32 v87, v84
	v_mov_b32_e32 v102, v90
	v_mov_b32_e32 v82, v91
	v_mov_b32_e32 v86, v92
	v_mov_b32_e32 v84, v93
.LBB0_151:
	v_mov_b64_e32 v[90:91], s[12:13]
	v_mad_i64_i32 v[88:89], s[0:1], v88, s43, v[90:91]
	v_pk_mul_f32 v[90:91], v[78:79], v[102:103]
	v_mov_b32_e32 v92, v85
	v_sub_f32_e32 v0, v90, v91
	v_mov_b32_e32 v90, v103
	v_mov_b32_e32 v91, v102
	v_pk_mul_f32 v[78:79], v[78:79], v[90:91]
	v_mov_b32_e32 v93, v84
	v_add_f32_e32 v94, v78, v79
	v_pk_mul_f32 v[78:79], v[80:81], v[82:83]
	v_lshl_add_u64 v[88:89], v[158:159], 1, v[88:89]
	v_sub_f32_e32 v95, v78, v79
	v_mov_b32_e32 v78, v83
	v_mov_b32_e32 v79, v82
	v_pk_mul_f32 v[80:81], v[80:81], v[78:79]
	s_nop 0
	v_add_f32_e32 v96, v80, v81
	v_pk_mul_f32 v[80:81], v[74:75], v[86:87]
	s_nop 0
	v_sub_f32_e32 v97, v80, v81
	v_mov_b32_e32 v80, v87
	v_mov_b32_e32 v81, v86
	v_pk_mul_f32 v[74:75], v[74:75], v[80:81]
	s_nop 0
	v_add_f32_e32 v98, v74, v75
	v_pk_mul_f32 v[74:75], v[76:77], v[84:85]
	s_nop 0
	v_sub_f32_e32 v99, v74, v75
	v_pk_mul_f32 v[74:75], v[76:77], v[92:93]
	s_nop 0
	v_add_f32_e32 v77, v74, v75
	v_cvt_pk_bf16_f32 v74, v0, v94
	v_cvt_pk_bf16_f32 v75, v95, v96
	v_cvt_pk_bf16_f32 v76, v97, v98
	v_cvt_pk_bf16_f32 v77, v99, v77
	global_store_dwordx4 v[88:89], v[74:77], off sc1 nt
	s_nop 1
	v_pk_mul_f32 v[74:75], v[70:71], v[102:103]
	v_pk_mul_f32 v[70:71], v[70:71], v[90:91]
	v_sub_f32_e32 v0, v74, v75
	v_add_f32_e32 v74, v70, v71
	v_pk_mul_f32 v[70:71], v[72:73], v[82:83]
	s_nop 0
	v_sub_f32_e32 v75, v70, v71
	v_pk_mul_f32 v[70:71], v[72:73], v[78:79]
	s_nop 0
	v_add_f32_e32 v72, v70, v71
	v_pk_mul_f32 v[70:71], v[66:67], v[86:87]
	v_pk_mul_f32 v[66:67], v[66:67], v[80:81]
	v_sub_f32_e32 v70, v70, v71
	v_add_f32_e32 v71, v66, v67
	v_pk_mul_f32 v[66:67], v[68:69], v[84:85]
	s_nop 0
	v_sub_f32_e32 v73, v66, v67
	v_pk_mul_f32 v[66:67], v[68:69], v[92:93]
	s_nop 0
	v_add_f32_e32 v69, v66, v67
	v_cvt_pk_bf16_f32 v66, v0, v74
	v_cvt_pk_bf16_f32 v67, v75, v72
	v_cvt_pk_bf16_f32 v68, v70, v71
	v_cvt_pk_bf16_f32 v69, v73, v69
	global_store_dwordx4 v[88:89], v[66:69], off offset:256 sc1 nt
	v_add_u32_e32 v76, 0x80, v170
	v_mov_b32_e32 v70, 1.0
	v_mov_b32_e32 v71, 0
	s_and_b64 vcc, exec, s[8:9]
	v_mov_b32_e32 v75, 0
	v_mov_b32_e32 v67, 0
	v_mov_b32_e32 v73, 0
	v_mov_b32_e32 v69, 0
	v_mov_b32_e32 v74, 1.0
	v_mov_b32_e32 v66, 1.0
	v_mov_b32_e32 v72, 1.0
	v_mov_b32_e32 v68, 1.0
	s_cbranch_vccnz .LBB0_153
	s_waitcnt vmcnt(14)
	v_mov_b32_e32 v66, v228
	v_mov_b32_e32 v67, v229
	v_mov_b32_e32 v68, v230
	v_mov_b32_e32 v69, v231
	v_mov_b32_e32 v78, v232
	v_mov_b32_e32 v79, v233
	v_mov_b32_e32 v80, v234
	v_mov_b32_e32 v81, v235
	v_mov_b32_e32 v75, v66
	v_mov_b32_e32 v73, v68
	v_mov_b32_e32 v74, v78
	v_mov_b32_e32 v66, v79
	v_mov_b32_e32 v72, v80
	v_mov_b32_e32 v68, v81
.LBB0_153:
	v_mov_b64_e32 v[78:79], s[12:13]
	v_mad_i64_i32 v[76:77], s[0:1], v76, s43, v[78:79]
	v_pk_mul_f32 v[78:79], v[62:63], v[74:75]
	v_mov_b32_e32 v80, v69
	v_sub_f32_e32 v0, v78, v79
	v_mov_b32_e32 v78, v75
	v_mov_b32_e32 v79, v74
	v_pk_mul_f32 v[62:63], v[62:63], v[78:79]
	v_mov_b32_e32 v81, v68
	v_add_f32_e32 v82, v62, v63
	v_pk_mul_f32 v[62:63], v[64:65], v[66:67]
	v_lshl_add_u64 v[76:77], v[158:159], 1, v[76:77]
	v_sub_f32_e32 v83, v62, v63
	v_mov_b32_e32 v62, v67
	v_mov_b32_e32 v63, v66
	v_pk_mul_f32 v[64:65], v[64:65], v[62:63]
	s_nop 0
	v_add_f32_e32 v84, v64, v65
	v_pk_mul_f32 v[64:65], v[58:59], v[72:73]
	s_nop 0
	v_sub_f32_e32 v85, v64, v65
	v_mov_b32_e32 v64, v73
	v_mov_b32_e32 v65, v72
	v_pk_mul_f32 v[58:59], v[58:59], v[64:65]
	s_nop 0
	v_add_f32_e32 v86, v58, v59
	v_pk_mul_f32 v[58:59], v[60:61], v[68:69]
	s_nop 0
	v_sub_f32_e32 v87, v58, v59
	v_pk_mul_f32 v[58:59], v[60:61], v[80:81]
	s_nop 0
	v_add_f32_e32 v61, v58, v59
	v_cvt_pk_bf16_f32 v58, v0, v82
	v_cvt_pk_bf16_f32 v59, v83, v84
	v_cvt_pk_bf16_f32 v60, v85, v86
	v_cvt_pk_bf16_f32 v61, v87, v61
	global_store_dwordx4 v[76:77], v[58:61], off sc1 nt
	s_nop 1
	v_pk_mul_f32 v[58:59], v[54:55], v[74:75]
	v_pk_mul_f32 v[54:55], v[54:55], v[78:79]
	v_sub_f32_e32 v0, v58, v59
	v_add_f32_e32 v58, v54, v55
	v_pk_mul_f32 v[54:55], v[56:57], v[66:67]
	s_nop 0
	v_sub_f32_e32 v59, v54, v55
	v_pk_mul_f32 v[54:55], v[56:57], v[62:63]
	s_nop 0
	v_add_f32_e32 v56, v54, v55
	v_pk_mul_f32 v[54:55], v[50:51], v[72:73]
	v_pk_mul_f32 v[50:51], v[50:51], v[64:65]
	v_sub_f32_e32 v54, v54, v55
	v_add_f32_e32 v55, v50, v51
	v_pk_mul_f32 v[50:51], v[52:53], v[68:69]
	s_nop 0
	v_sub_f32_e32 v57, v50, v51
	v_pk_mul_f32 v[50:51], v[52:53], v[80:81]
	s_nop 0
	v_add_f32_e32 v53, v50, v51
	v_cvt_pk_bf16_f32 v50, v0, v58
	v_cvt_pk_bf16_f32 v51, v59, v56
	v_cvt_pk_bf16_f32 v52, v54, v55
	v_cvt_pk_bf16_f32 v53, v57, v53
	global_store_dwordx4 v[76:77], v[50:53], off offset:256 sc1 nt
	v_add_u32_e32 v56, 0x90, v170
	s_and_b64 vcc, exec, s[8:9]
	v_mov_b32_e32 v51, 0
	v_mov_b32_e32 v55, 0
	v_mov_b32_e32 v53, 0
	v_mov_b32_e32 v50, 1.0
	v_mov_b32_e32 v54, 1.0
	v_mov_b32_e32 v52, 1.0
	s_cbranch_vccnz .LBB0_155
	s_waitcnt vmcnt(14)
	v_mov_b32_e32 v50, v236
	v_mov_b32_e32 v51, v237
	v_mov_b32_e32 v52, v238
	v_mov_b32_e32 v53, v239
	v_mov_b32_e32 v58, v240
	v_mov_b32_e32 v59, v241
	v_mov_b32_e32 v60, v242
	v_mov_b32_e32 v61, v243
	v_mov_b32_e32 v71, v50
	v_mov_b32_e32 v55, v52
	v_mov_b32_e32 v70, v58
	v_mov_b32_e32 v50, v59
	v_mov_b32_e32 v54, v60
	v_mov_b32_e32 v52, v61
.LBB0_155:
	v_mov_b64_e32 v[58:59], s[12:13]
	v_mad_i64_i32 v[56:57], s[0:1], v56, s43, v[58:59]
	v_pk_mul_f32 v[58:59], v[46:47], v[70:71]
	v_mov_b32_e32 v60, v53
	v_sub_f32_e32 v0, v58, v59
	v_mov_b32_e32 v58, v71
	v_mov_b32_e32 v59, v70
	v_pk_mul_f32 v[46:47], v[46:47], v[58:59]
	v_mov_b32_e32 v61, v52
	v_add_f32_e32 v62, v46, v47
	v_pk_mul_f32 v[46:47], v[48:49], v[50:51]
	v_lshl_add_u64 v[56:57], v[158:159], 1, v[56:57]
	v_sub_f32_e32 v63, v46, v47
	v_mov_b32_e32 v46, v51
	v_mov_b32_e32 v47, v50
	v_pk_mul_f32 v[48:49], v[48:49], v[46:47]
	s_nop 0
	v_add_f32_e32 v64, v48, v49
	v_pk_mul_f32 v[48:49], v[42:43], v[54:55]
	s_nop 0
	v_sub_f32_e32 v65, v48, v49
	v_mov_b32_e32 v48, v55
	v_mov_b32_e32 v49, v54
	v_pk_mul_f32 v[42:43], v[42:43], v[48:49]
	s_nop 0
	v_add_f32_e32 v66, v42, v43
	v_pk_mul_f32 v[42:43], v[44:45], v[52:53]
	s_nop 0
	v_sub_f32_e32 v67, v42, v43
	v_pk_mul_f32 v[42:43], v[44:45], v[60:61]
	s_nop 0
	v_add_f32_e32 v45, v42, v43
	v_cvt_pk_bf16_f32 v42, v0, v62
	v_cvt_pk_bf16_f32 v43, v63, v64
	v_cvt_pk_bf16_f32 v44, v65, v66
	v_cvt_pk_bf16_f32 v45, v67, v45
	global_store_dwordx4 v[56:57], v[42:45], off sc1 nt
	s_nop 1
	v_pk_mul_f32 v[42:43], v[38:39], v[70:71]
	v_pk_mul_f32 v[38:39], v[38:39], v[58:59]
	v_sub_f32_e32 v0, v42, v43
	v_add_f32_e32 v42, v38, v39
	v_pk_mul_f32 v[38:39], v[40:41], v[50:51]
	s_nop 0
	v_sub_f32_e32 v43, v38, v39
	v_pk_mul_f32 v[38:39], v[40:41], v[46:47]
	s_nop 0
	v_add_f32_e32 v40, v38, v39
	v_pk_mul_f32 v[38:39], v[34:35], v[54:55]
	v_pk_mul_f32 v[34:35], v[34:35], v[48:49]
	v_sub_f32_e32 v38, v38, v39
	v_add_f32_e32 v39, v34, v35
	v_pk_mul_f32 v[34:35], v[36:37], v[52:53]
	s_nop 0
	v_sub_f32_e32 v41, v34, v35
	v_pk_mul_f32 v[34:35], v[36:37], v[60:61]
	s_nop 0
	v_add_f32_e32 v37, v34, v35
	v_cvt_pk_bf16_f32 v34, v0, v42
	v_cvt_pk_bf16_f32 v35, v43, v40
	v_cvt_pk_bf16_f32 v36, v38, v39
	v_cvt_pk_bf16_f32 v37, v41, v37
	global_store_dwordx4 v[56:57], v[34:37], off offset:256 sc1 nt
	v_add_u32_e32 v44, 0xa0, v170
	v_mov_b32_e32 v38, 1.0
	v_mov_b32_e32 v39, 0
	s_and_b64 vcc, exec, s[8:9]
	v_mov_b32_e32 v43, 0
	v_mov_b32_e32 v35, 0
	v_mov_b32_e32 v41, 0
	v_mov_b32_e32 v37, 0
	v_mov_b32_e32 v42, 1.0
	v_mov_b32_e32 v34, 1.0
	v_mov_b32_e32 v40, 1.0
	v_mov_b32_e32 v36, 1.0
	s_cbranch_vccnz .LBB0_157
	s_waitcnt vmcnt(10)
	v_mov_b32_e32 v34, v184
	v_mov_b32_e32 v35, v185
	v_mov_b32_e32 v36, v186
	v_mov_b32_e32 v37, v187
	v_mov_b32_e32 v46, v188
	v_mov_b32_e32 v47, v189
	v_mov_b32_e32 v48, v190
	v_mov_b32_e32 v49, v191
	v_mov_b32_e32 v43, v34
	v_mov_b32_e32 v41, v36
	v_mov_b32_e32 v42, v46
	v_mov_b32_e32 v34, v47
	v_mov_b32_e32 v40, v48
	v_mov_b32_e32 v36, v49
.LBB0_157:
	v_mov_b64_e32 v[46:47], s[12:13]
	v_mad_i64_i32 v[44:45], s[0:1], v44, s43, v[46:47]
	v_pk_mul_f32 v[46:47], v[30:31], v[42:43]
	v_mov_b32_e32 v48, v37
	v_sub_f32_e32 v0, v46, v47
	v_mov_b32_e32 v46, v43
	v_mov_b32_e32 v47, v42
	v_pk_mul_f32 v[30:31], v[30:31], v[46:47]
	v_mov_b32_e32 v49, v36
	v_add_f32_e32 v50, v30, v31
	v_pk_mul_f32 v[30:31], v[32:33], v[34:35]
	v_lshl_add_u64 v[44:45], v[158:159], 1, v[44:45]
	v_sub_f32_e32 v51, v30, v31
	v_mov_b32_e32 v30, v35
	v_mov_b32_e32 v31, v34
	v_pk_mul_f32 v[32:33], v[32:33], v[30:31]
	s_nop 0
	v_add_f32_e32 v52, v32, v33
	v_pk_mul_f32 v[32:33], v[26:27], v[40:41]
	s_nop 0
	v_sub_f32_e32 v53, v32, v33
	v_mov_b32_e32 v32, v41
	v_mov_b32_e32 v33, v40
	v_pk_mul_f32 v[26:27], v[26:27], v[32:33]
	s_nop 0
	v_add_f32_e32 v54, v26, v27
	v_pk_mul_f32 v[26:27], v[28:29], v[36:37]
	s_nop 0
	v_sub_f32_e32 v55, v26, v27
	v_pk_mul_f32 v[26:27], v[28:29], v[48:49]
	s_nop 0
	v_add_f32_e32 v29, v26, v27
	v_cvt_pk_bf16_f32 v26, v0, v50
	v_cvt_pk_bf16_f32 v27, v51, v52
	v_cvt_pk_bf16_f32 v28, v53, v54
	v_cvt_pk_bf16_f32 v29, v55, v29
	global_store_dwordx4 v[44:45], v[26:29], off sc1 nt
	s_nop 1
	v_pk_mul_f32 v[26:27], v[22:23], v[42:43]
	v_pk_mul_f32 v[22:23], v[22:23], v[46:47]
	v_sub_f32_e32 v0, v26, v27
	v_add_f32_e32 v26, v22, v23
	v_pk_mul_f32 v[22:23], v[24:25], v[34:35]
	s_nop 0
	v_sub_f32_e32 v27, v22, v23
	v_pk_mul_f32 v[22:23], v[24:25], v[30:31]
	s_nop 0
	v_add_f32_e32 v24, v22, v23
	v_pk_mul_f32 v[22:23], v[18:19], v[40:41]
	v_pk_mul_f32 v[18:19], v[18:19], v[32:33]
	v_sub_f32_e32 v22, v22, v23
	v_add_f32_e32 v23, v18, v19
	v_pk_mul_f32 v[18:19], v[20:21], v[36:37]
	s_nop 0
	v_sub_f32_e32 v25, v18, v19
	v_pk_mul_f32 v[18:19], v[20:21], v[48:49]
	s_nop 0
	v_add_f32_e32 v21, v18, v19
	v_cvt_pk_bf16_f32 v18, v0, v26
	v_cvt_pk_bf16_f32 v19, v27, v24
	v_cvt_pk_bf16_f32 v20, v22, v23
	v_cvt_pk_bf16_f32 v21, v25, v21
	global_store_dwordx4 v[44:45], v[18:21], off offset:256 sc1 nt
	v_add_u32_e32 v24, 0xb0, v170
	s_and_b64 vcc, exec, s[8:9]
	v_mov_b32_e32 v19, 0
	v_mov_b32_e32 v23, 0
	v_mov_b32_e32 v21, 0
	v_mov_b32_e32 v18, 1.0
	v_mov_b32_e32 v22, 1.0
	v_mov_b32_e32 v20, 1.0
	s_cbranch_vccnz .LBB0_159
	s_waitcnt vmcnt(10)
	v_mov_b32_e32 v18, v192
	v_mov_b32_e32 v19, v193
	v_mov_b32_e32 v20, v194
	v_mov_b32_e32 v21, v195
	v_mov_b32_e32 v26, v196
	v_mov_b32_e32 v27, v197
	v_mov_b32_e32 v28, v198
	v_mov_b32_e32 v29, v199
	v_mov_b32_e32 v39, v18
	v_mov_b32_e32 v23, v20
	v_mov_b32_e32 v38, v26
	v_mov_b32_e32 v18, v27
	v_mov_b32_e32 v22, v28
	v_mov_b32_e32 v20, v29
.LBB0_159:
	v_mov_b64_e32 v[26:27], s[12:13]
	v_mad_i64_i32 v[24:25], s[0:1], v24, s43, v[26:27]
	v_pk_mul_f32 v[26:27], v[14:15], v[38:39]
	v_mov_b32_e32 v28, v21
	v_sub_f32_e32 v0, v26, v27
	v_mov_b32_e32 v26, v39
	v_mov_b32_e32 v27, v38
	v_pk_mul_f32 v[14:15], v[14:15], v[26:27]
	v_mov_b32_e32 v29, v20
	v_add_f32_e32 v30, v14, v15
	v_pk_mul_f32 v[14:15], v[16:17], v[18:19]
	v_lshl_add_u64 v[24:25], v[158:159], 1, v[24:25]
	v_sub_f32_e32 v31, v14, v15
	v_mov_b32_e32 v14, v19
	v_mov_b32_e32 v15, v18
	v_pk_mul_f32 v[16:17], v[16:17], v[14:15]
	s_nop 0
	v_add_f32_e32 v32, v16, v17
	v_pk_mul_f32 v[16:17], v[10:11], v[22:23]
	s_nop 0
	v_sub_f32_e32 v33, v16, v17
	v_mov_b32_e32 v16, v23
	v_mov_b32_e32 v17, v22
	v_pk_mul_f32 v[10:11], v[10:11], v[16:17]
	s_nop 0
	v_add_f32_e32 v34, v10, v11
	v_pk_mul_f32 v[10:11], v[12:13], v[20:21]
	s_nop 0
	v_sub_f32_e32 v35, v10, v11
	v_pk_mul_f32 v[10:11], v[12:13], v[28:29]
	s_nop 0
	v_add_f32_e32 v13, v10, v11
	v_cvt_pk_bf16_f32 v10, v0, v30
	v_cvt_pk_bf16_f32 v11, v31, v32
	v_cvt_pk_bf16_f32 v12, v33, v34
	v_cvt_pk_bf16_f32 v13, v35, v13
	global_store_dwordx4 v[24:25], v[10:13], off sc1 nt
	s_nop 1
	v_pk_mul_f32 v[10:11], v[6:7], v[38:39]
	v_pk_mul_f32 v[6:7], v[6:7], v[26:27]
	v_sub_f32_e32 v0, v10, v11
	v_add_f32_e32 v10, v6, v7
	v_pk_mul_f32 v[6:7], v[8:9], v[18:19]
	s_nop 0
	v_sub_f32_e32 v11, v6, v7
	v_pk_mul_f32 v[6:7], v[8:9], v[14:15]
	s_nop 0
	v_add_f32_e32 v8, v6, v7
	v_pk_mul_f32 v[6:7], v[2:3], v[22:23]
	v_pk_mul_f32 v[2:3], v[2:3], v[16:17]
	v_sub_f32_e32 v6, v6, v7
	v_add_f32_e32 v7, v2, v3
	v_pk_mul_f32 v[2:3], v[4:5], v[20:21]
	s_nop 0
	v_sub_f32_e32 v9, v2, v3
	v_pk_mul_f32 v[2:3], v[4:5], v[28:29]
	s_nop 0
	v_add_f32_e32 v5, v2, v3
	v_cvt_pk_bf16_f32 v2, v0, v10
	v_cvt_pk_bf16_f32 v3, v11, v8
	v_cvt_pk_bf16_f32 v4, v6, v7
	v_cvt_pk_bf16_f32 v5, v9, v5
	global_store_dwordx4 v[24:25], v[2:5], off offset:256 sc1 nt

.Lepi_fast:
	v_lshl_or_b32 v158, s55, 8, v168
	v_ashrrev_i32_e32 v159, 31, v158
	v_mov_b64_e32 v[172:173], s[12:13]
	v_mad_i64_i32 v[172:173], s[0:1], v170, s43, v[172:173]
	v_cvt_pk_bf16_f32 v126, v126, v127
	v_cvt_pk_bf16_f32 v127, v128, v129
	v_cvt_pk_bf16_f32 v128, v122, v123
	v_cvt_pk_bf16_f32 v129, v124, v125
	v_lshl_add_u64 v[172:173], v[158:159], 1, v[172:173]
	v_cvt_pk_bf16_f32 v118, v118, v119
	v_cvt_pk_bf16_f32 v119, v120, v121
	v_cvt_pk_bf16_f32 v120, v114, v115
	v_cvt_pk_bf16_f32 v121, v116, v117
	global_store_dwordx4 v[172:173], v[126:129], off sc1 nt
	global_store_dwordx4 v[172:173], v[118:121], off offset:256 sc1 nt
	v_add_u32_e32 v174, 16, v170
	v_mov_b64_e32 v[172:173], s[12:13]
	v_mad_i64_i32 v[172:173], s[0:1], v174, s43, v[172:173]
	v_cvt_pk_bf16_f32 v110, v110, v111
	v_cvt_pk_bf16_f32 v111, v112, v113
	v_cvt_pk_bf16_f32 v112, v106, v107
	v_cvt_pk_bf16_f32 v113, v108, v109
	v_lshl_add_u64 v[172:173], v[158:159], 1, v[172:173]
	v_cvt_pk_bf16_f32 v102, v102, v103
	v_cvt_pk_bf16_f32 v103, v104, v105
	v_cvt_pk_bf16_f32 v104, v98, v99
	v_cvt_pk_bf16_f32 v105, v100, v101
	global_store_dwordx4 v[172:173], v[110:113], off sc1 nt
	global_store_dwordx4 v[172:173], v[102:105], off offset:256 sc1 nt
	v_add_u32_e32 v174, 32, v170
	v_mov_b64_e32 v[172:173], s[12:13]
	v_mad_i64_i32 v[172:173], s[0:1], v174, s43, v[172:173]
	v_cvt_pk_bf16_f32 v94, v94, v95
	v_cvt_pk_bf16_f32 v95, v96, v97
	v_cvt_pk_bf16_f32 v96, v90, v91
	v_cvt_pk_bf16_f32 v97, v92, v93
	v_lshl_add_u64 v[172:173], v[158:159], 1, v[172:173]
	v_cvt_pk_bf16_f32 v86, v86, v87
	v_cvt_pk_bf16_f32 v87, v88, v89
	v_cvt_pk_bf16_f32 v88, v82, v83
	v_cvt_pk_bf16_f32 v89, v84, v85
	global_store_dwordx4 v[172:173], v[94:97], off sc1 nt
	global_store_dwordx4 v[172:173], v[86:89], off offset:256 sc1 nt
	v_add_u32_e32 v174, 48, v170
	v_mov_b64_e32 v[172:173], s[12:13]
	v_mad_i64_i32 v[172:173], s[0:1], v174, s43, v[172:173]
	v_cvt_pk_bf16_f32 v78, v78, v79
	v_cvt_pk_bf16_f32 v79, v80, v81
	v_cvt_pk_bf16_f32 v80, v74, v75
	v_cvt_pk_bf16_f32 v81, v76, v77
	v_lshl_add_u64 v[172:173], v[158:159], 1, v[172:173]
	v_cvt_pk_bf16_f32 v70, v70, v71
	v_cvt_pk_bf16_f32 v71, v72, v73
	v_cvt_pk_bf16_f32 v72, v66, v67
	v_cvt_pk_bf16_f32 v73, v68, v69
	global_store_dwordx4 v[172:173], v[78:81], off sc1 nt
	global_store_dwordx4 v[172:173], v[70:73], off offset:256 sc1 nt
	v_add_u32_e32 v174, 0x80, v170
	v_mov_b64_e32 v[172:173], s[12:13]
	v_mad_i64_i32 v[172:173], s[0:1], v174, s43, v[172:173]
	v_cvt_pk_bf16_f32 v62, v62, v63
	v_cvt_pk_bf16_f32 v63, v64, v65
	v_cvt_pk_bf16_f32 v64, v58, v59
	v_cvt_pk_bf16_f32 v65, v60, v61
	v_lshl_add_u64 v[172:173], v[158:159], 1, v[172:173]
	v_cvt_pk_bf16_f32 v54, v54, v55
	v_cvt_pk_bf16_f32 v55, v56, v57
	v_cvt_pk_bf16_f32 v56, v50, v51
	v_cvt_pk_bf16_f32 v57, v52, v53
	global_store_dwordx4 v[172:173], v[62:65], off sc1 nt
	global_store_dwordx4 v[172:173], v[54:57], off offset:256 sc1 nt
	v_add_u32_e32 v174, 0x90, v170
	v_mov_b64_e32 v[172:173], s[12:13]
	v_mad_i64_i32 v[172:173], s[0:1], v174, s43, v[172:173]
	v_cvt_pk_bf16_f32 v46, v46, v47
	v_cvt_pk_bf16_f32 v47, v48, v49
	v_cvt_pk_bf16_f32 v48, v42, v43
	v_cvt_pk_bf16_f32 v49, v44, v45
	v_lshl_add_u64 v[172:173], v[158:159], 1, v[172:173]
	v_cvt_pk_bf16_f32 v38, v38, v39
	v_cvt_pk_bf16_f32 v39, v40, v41
	v_cvt_pk_bf16_f32 v40, v34, v35
	v_cvt_pk_bf16_f32 v41, v36, v37
	global_store_dwordx4 v[172:173], v[46:49], off sc1 nt
	global_store_dwordx4 v[172:173], v[38:41], off offset:256 sc1 nt
	v_add_u32_e32 v174, 0xa0, v170
	v_mov_b64_e32 v[172:173], s[12:13]
	v_mad_i64_i32 v[172:173], s[0:1], v174, s43, v[172:173]
	v_cvt_pk_bf16_f32 v30, v30, v31
	v_cvt_pk_bf16_f32 v31, v32, v33
	v_cvt_pk_bf16_f32 v32, v26, v27
	v_cvt_pk_bf16_f32 v33, v28, v29
	v_lshl_add_u64 v[172:173], v[158:159], 1, v[172:173]
	v_cvt_pk_bf16_f32 v22, v22, v23
	v_cvt_pk_bf16_f32 v23, v24, v25
	v_cvt_pk_bf16_f32 v24, v18, v19
	v_cvt_pk_bf16_f32 v25, v20, v21
	global_store_dwordx4 v[172:173], v[30:33], off sc1 nt
	global_store_dwordx4 v[172:173], v[22:25], off offset:256 sc1 nt
	v_add_u32_e32 v174, 0xb0, v170
	v_mov_b64_e32 v[172:173], s[12:13]
	v_mad_i64_i32 v[172:173], s[0:1], v174, s43, v[172:173]
	v_cvt_pk_bf16_f32 v14, v14, v15
	v_cvt_pk_bf16_f32 v15, v16, v17
	v_cvt_pk_bf16_f32 v16, v10, v11
	v_cvt_pk_bf16_f32 v17, v12, v13
	v_lshl_add_u64 v[172:173], v[158:159], 1, v[172:173]
	v_cvt_pk_bf16_f32 v6, v6, v7
	v_cvt_pk_bf16_f32 v7, v8, v9
	v_cvt_pk_bf16_f32 v8, v2, v3
	v_cvt_pk_bf16_f32 v9, v4, v5
	global_store_dwordx4 v[172:173], v[14:17], off sc1 nt
	global_store_dwordx4 v[172:173], v[6:9], off offset:256 sc1 nt
	s_branch .Lepi_join

.LBB0_834:
	s_add_i32 s8, s68, s0
	v_add_co_u32_e32 v12, vcc, 0x8000000, v100
	s_ashr_i32 s9, s8, 31
	v_lshl_add_u64 v[10:11], s[16:17], 0, v[80:81]
	v_addc_co_u32_e32 v13, vcc, 0, v101, vcc
	s_lshl_b64 s[10:11], s[8:9], 12
	flat_load_dwordx2 v[8:9], v[12:13] nt
	global_load_dwordx4 v[2:5], v[10:11], off nt
	flat_load_dwordx2 v[46:47], v[12:13] offset:512 nt
	global_load_dwordx4 v[30:33], v[10:11], off offset:1024 nt
	flat_load_dwordx2 v[48:49], v[12:13] offset:1024 nt
	global_load_dwordx4 v[34:37], v[10:11], off offset:2048 nt
	flat_load_dwordx2 v[58:59], v[12:13] offset:1536 nt
	global_load_dwordx4 v[26:29], v[10:11], off offset:3072 nt
	flat_load_dwordx2 v[60:61], v[12:13] offset:2048 nt
	v_add_co_u32_e32 v10, vcc, s71, v10
	v_lshl_add_u64 v[6:7], v[84:85], 0, s[10:11]
	s_nop 0
	v_addc_co_u32_e32 v11, vcc, 0, v11, vcc
	s_lshl_b64 s[14:15], s[8:9], 13
	global_load_dwordx4 v[22:25], v[10:11], off nt
	flat_load_dwordx2 v[110:111], v[12:13] offset:2560 nt
	global_load_dwordx4 v[14:17], v[10:11], off offset:1024 nt
	flat_load_dwordx2 v[108:109], v[12:13] offset:3072 nt
	global_load_dwordx4 v[18:21], v[10:11], off offset:2048 nt
	flat_load_dwordx2 v[106:107], v[12:13] offset:3584 nt
	global_load_dwordx4 v[62:65], v[10:11], off offset:3072 nt
	v_lshl_add_u64 v[10:11], v[82:83], 0, s[14:15]
	flat_load_dwordx2 v[50:51], v[6:7] nt
	global_load_dwordx4 v[124:127], v[10:11], off nt
	flat_load_dwordx2 v[104:105], v[6:7] offset:512 nt
	global_load_dwordx4 v[128:131], v[10:11], off offset:1024 nt
	flat_load_dwordx2 v[52:53], v[6:7] offset:1024 nt
	global_load_dwordx4 v[42:45], v[10:11], off offset:2048 nt
	flat_load_dwordx2 v[102:103], v[6:7] offset:1536 nt
	global_load_dwordx4 v[54:57], v[10:11], off offset:3072 nt
	flat_load_dwordx2 v[118:119], v[6:7] offset:2048 nt
	v_add_co_u32_e32 v10, vcc, s71, v10
	s_add_i32 s0, s0, s58
	s_nop 0
	v_addc_co_u32_e32 v11, vcc, 0, v11, vcc
	global_load_dwordx4 v[38:41], v[10:11], off nt
	flat_load_dwordx2 v[116:117], v[6:7] offset:2560 nt
	global_load_dwordx4 v[74:77], v[10:11], off offset:1024 nt
	flat_load_dwordx2 v[114:115], v[6:7] offset:3072 nt
	global_load_dwordx4 v[70:73], v[10:11], off offset:2048 nt
	flat_load_dwordx2 v[112:113], v[6:7] offset:3584 nt
	global_load_dwordx4 v[66:69], v[10:11], off offset:3072 nt
	s_waitcnt vmcnt(0) lgkmcnt(0)
	v_lshlrev_b32_e32 v6, 16, v8
	v_and_b32_e32 v7, 0xffff0000, v8
	v_pk_add_f32 v[10:11], v[2:3], v[6:7]
	v_lshlrev_b32_e32 v2, 16, v9
	v_and_b32_e32 v3, 0xffff0000, v9
	v_pk_add_f32 v[12:13], v[4:5], v[2:3]
	v_lshlrev_b32_e32 v2, 16, v50
	v_and_b32_e32 v3, 0xffff0000, v50
	v_pk_add_f32 v[6:7], v[124:125], v[2:3]
	v_lshlrev_b32_e32 v2, 16, v51
	v_and_b32_e32 v3, 0xffff0000, v51
	v_pk_add_f32 v[8:9], v[126:127], v[2:3]
	v_lshlrev_b32_e32 v2, 16, v104
	v_and_b32_e32 v3, 0xffff0000, v104
	v_lshlrev_b32_e32 v50, 16, v46
	v_and_b32_e32 v51, 0xffff0000, v46
	v_pk_add_f32 v[2:3], v[128:129], v[2:3]
	v_lshlrev_b32_e32 v4, 16, v105
	v_and_b32_e32 v5, 0xffff0000, v105
	v_pk_add_f32 v[30:31], v[30:31], v[50:51]
	v_and_b32_e32 v51, 0xffff0000, v47
	v_lshlrev_b32_e32 v50, 16, v47
	v_pk_add_f32 v[4:5], v[130:131], v[4:5]
	v_pk_add_f32 v[32:33], v[32:33], v[50:51]
	v_mov_b32_e32 v50, v7
	v_mov_b32_e32 v51, v3
	v_mov_b32_e32 v46, v6
	v_mov_b32_e32 v47, v2
	v_pk_mul_f32 v[50:51], v[50:51], v[50:51]
	v_mov_b32_e32 v130, v9
	v_mov_b32_e32 v131, v5
	v_pk_fma_f32 v[46:47], v[46:47], v[46:47], v[50:51]
	v_mov_b32_e32 v50, v8
	v_mov_b32_e32 v51, v4
	v_pk_mul_f32 v[130:131], v[130:131], v[130:131]
	v_pk_mul_f32 v[124:125], v[10:11], v[10:11]
	v_pk_fma_f32 v[50:51], v[50:51], v[50:51], v[130:131]
	v_pk_mul_f32 v[126:127], v[12:13], v[12:13]
	v_pk_add_f32 v[46:47], v[46:47], v[50:51]
	v_mul_f32_e32 v0, v31, v31
	v_pk_add_f32 v[130:131], v[46:47], v[46:47] op_sel:[0,1] op_sel_hi:[1,0]
	v_lshlrev_b32_e32 v46, 16, v48
	v_and_b32_e32 v47, 0xffff0000, v48
	v_pk_add_f32 v[46:47], v[34:35], v[46:47]
	v_lshlrev_b32_e32 v34, 16, v49
	v_and_b32_e32 v35, 0xffff0000, v49
	v_pk_add_f32 v[48:49], v[36:37], v[34:35]
	v_lshlrev_b32_e32 v34, 16, v52
	v_and_b32_e32 v35, 0xffff0000, v52
	v_pk_mov_b32 v[36:37], v[124:125], v[46:47] op_sel:[1,0]
	v_pk_add_f32 v[50:51], v[42:43], v[34:35]
	v_pk_fma_f32 v[42:43], v[10:11], v[10:11], v[36:37]
	v_pk_mul_f32 v[36:37], v[46:47], v[36:37] op_sel_hi:[0,1]
	v_pk_fma_f32 v[104:105], v[30:31], v[30:31], v[0:1] op_sel_hi:[1,1,0]
	v_mul_f32_e32 v0, v33, v33
	v_lshlrev_b32_e32 v34, 16, v53
	v_and_b32_e32 v35, 0xffff0000, v53
	v_mov_b32_e32 v43, v37
	v_mov_b32_e32 v36, v127
	v_mov_b32_e32 v37, v47
	v_pk_fma_f32 v[128:129], v[32:33], v[32:33], v[0:1] op_sel_hi:[1,1,0]
	v_pk_add_f32 v[52:53], v[44:45], v[34:35]
	v_pk_mul_f32 v[34:35], v[48:49], v[48:49]
	v_pk_fma_f32 v[36:37], v[12:13], v[12:13], v[36:37]
	v_pk_mul_f32 v[44:45], v[46:47], v[46:47]
	v_mov_b32_e32 v105, v35
	v_mov_b32_e32 v37, v45
	v_mov_b32_e32 v129, v34
	v_pk_add_f32 v[36:37], v[42:43], v[36:37]
	v_pk_add_f32 v[34:35], v[104:105], v[128:129]
	v_mov_b32_e32 v42, v27
	v_pk_add_f32 v[34:35], v[36:37], v[34:35]
	v_mov_b32_e32 v36, v51
	v_mov_b32_e32 v37, v53
	v_pk_add_f32 v[124:125], v[34:35], v[34:35] op_sel:[0,1] op_sel_hi:[1,0]
	v_mov_b32_e32 v34, v50
	v_mov_b32_e32 v35, v52
	v_pk_mul_f32 v[36:37], v[36:37], v[36:37]
	v_mov_b32_e32 v43, v28
	v_pk_fma_f32 v[34:35], v[34:35], v[34:35], v[36:37]
	v_lshlrev_b32_e32 v36, 16, v102
	v_and_b32_e32 v37, 0xffff0000, v102
	v_pk_add_f32 v[54:55], v[54:55], v[36:37]
	v_lshlrev_b32_e32 v36, 16, v103
	v_and_b32_e32 v37, 0xffff0000, v103
	v_pk_add_f32 v[56:57], v[56:57], v[36:37]
	v_and_b32_e32 v36, 0xffff0000, v58
	v_lshlrev_b32_e32 v37, 16, v59
	v_pk_add_f32 v[102:103], v[42:43], v[36:37]
	v_lshlrev_b32_e32 v36, 16, v58
	v_and_b32_e32 v37, 0xffff0000, v59
	v_mov_b32_e32 v27, v29
	v_pk_add_f32 v[104:105], v[26:27], v[36:37]
	v_lshlrev_b32_e32 v36, 16, v118
	v_and_b32_e32 v37, 0xffff0000, v118
	v_pk_add_f32 v[42:43], v[38:39], v[36:37]
	v_lshlrev_b32_e32 v36, 16, v119
	v_and_b32_e32 v37, 0xffff0000, v119
	v_pk_mul_f32 v[26:27], v[102:103], v[102:103]
	v_mul_f32_e32 v0, v55, v55
	v_pk_add_f32 v[44:45], v[40:41], v[36:37]
	v_lshlrev_b32_e32 v36, 16, v60
	v_and_b32_e32 v37, 0xffff0000, v60
	v_pk_fma_f32 v[126:127], v[104:105], v[104:105], v[26:27]
	v_pk_fma_f32 v[26:27], v[54:55], v[54:55], v[0:1] op_sel_hi:[1,1,0]
	v_mul_f32_e32 v0, v57, v57
	v_pk_add_f32 v[58:59], v[22:23], v[36:37]
	v_and_b32_e32 v37, 0xffff0000, v61
	v_lshlrev_b32_e32 v36, 16, v61
	v_pk_add_f32 v[34:35], v[34:35], v[34:35] op_sel:[0,1] op_sel_hi:[1,0]
	v_pk_fma_f32 v[28:29], v[56:57], v[56:57], v[0:1] op_sel_hi:[1,1,0]
	v_pk_add_f32 v[60:61], v[24:25], v[36:37]
	v_pk_mul_f32 v[24:25], v[42:43], v[42:43]
	v_pk_mul_f32 v[36:37], v[44:45], v[44:45]
	v_mov_b32_e32 v131, v24
	v_mov_b32_e32 v35, v25
	v_mov_b32_e32 v27, v36
	v_mov_b32_e32 v29, v37
	v_pk_add_f32 v[24:25], v[130:131], v[34:35]
	v_pk_add_f32 v[26:27], v[26:27], v[28:29]
	v_mul_f32_e32 v0, v59, v59
	v_pk_add_f32 v[24:25], v[24:25], v[26:27]
	v_pk_fma_f32 v[22:23], v[58:59], v[58:59], v[0:1] op_sel_hi:[1,1,0]
	v_pk_add_f32 v[128:129], v[24:25], v[24:25] op_sel:[0,1] op_sel_hi:[1,0]
	v_lshlrev_b32_e32 v24, 16, v110
	v_and_b32_e32 v25, 0xffff0000, v110
	v_pk_add_f32 v[38:39], v[14:15], v[24:25]
	v_lshlrev_b32_e32 v14, 16, v111
	v_and_b32_e32 v15, 0xffff0000, v111
	v_pk_add_f32 v[40:41], v[16:17], v[14:15]
	v_lshlrev_b32_e32 v14, 16, v116
	v_and_b32_e32 v15, 0xffff0000, v116
	v_lshlrev_b32_e32 v24, 16, v108
	v_and_b32_e32 v25, 0xffff0000, v108
	v_pk_add_f32 v[34:35], v[74:75], v[14:15]
	v_lshlrev_b32_e32 v14, 16, v117
	v_and_b32_e32 v15, 0xffff0000, v117
	v_pk_add_f32 v[26:27], v[18:19], v[24:25]
	v_and_b32_e32 v19, 0xffff0000, v109
	v_lshlrev_b32_e32 v18, 16, v109
	v_mul_f32_e32 v0, v61, v61
	v_pk_add_f32 v[36:37], v[76:77], v[14:15]
	v_pk_add_f32 v[28:29], v[20:21], v[18:19]
	v_lshlrev_b32_e32 v18, 16, v107
	v_and_b32_e32 v19, 0xffff0000, v107
	v_pk_fma_f32 v[118:119], v[60:61], v[60:61], v[0:1] op_sel_hi:[1,1,0]
	v_mov_b32_e32 v16, v35
	v_mov_b32_e32 v17, v37
	v_pk_add_f32 v[24:25], v[64:65], v[18:19]
	v_lshlrev_b32_e32 v18, 16, v112
	v_and_b32_e32 v19, 0xffff0000, v112
	v_pk_mul_f32 v[74:75], v[38:39], v[38:39]
	v_mov_b32_e32 v14, v34
	v_mov_b32_e32 v15, v36
	v_pk_mul_f32 v[16:17], v[16:17], v[16:17]
	v_lshlrev_b32_e32 v119, 16, v106
	v_pk_add_f32 v[18:19], v[66:67], v[18:19]
	v_pk_add_f32 v[66:67], v[126:127], v[126:127] op_sel:[0,1] op_sel_hi:[1,0]
	v_pk_mul_f32 v[76:77], v[40:41], v[40:41]
	v_pk_fma_f32 v[14:15], v[14:15], v[14:15], v[16:17]
	v_and_b32_e32 v117, 0xffff0000, v106
	v_lshlrev_b32_e32 v20, 16, v113
	v_and_b32_e32 v21, 0xffff0000, v113
	v_mov_b32_e32 v125, v62
	v_mov_b32_e32 v67, v119
	v_mov_b32_e32 v23, v62
	v_mov_b32_e32 v62, v74
	v_mov_b32_e32 v116, v75
	v_pk_add_f32 v[110:111], v[14:15], v[14:15] op_sel:[0,1] op_sel_hi:[1,0]
	v_lshlrev_b32_e32 v14, 16, v114
	v_and_b32_e32 v15, 0xffff0000, v114
	v_mul_f32_e32 v0, v27, v27
	v_pk_add_f32 v[20:21], v[68:69], v[20:21]
	v_pk_add_f32 v[66:67], v[124:125], v[66:67]
	v_pk_add_f32 v[68:69], v[22:23], v[118:119]
	v_pk_add_f32 v[22:23], v[62:63], v[116:117]
	v_mov_b32_e32 v62, v77
	v_mov_b32_e32 v77, v117
	v_pk_add_f32 v[14:15], v[70:71], v[14:15]
	v_lshlrev_b32_e32 v16, 16, v115
	v_and_b32_e32 v17, 0xffff0000, v115
	v_pk_fma_f32 v[70:71], v[26:27], v[26:27], v[0:1] op_sel_hi:[1,1,0]
	v_mul_f32_e32 v0, v29, v29
	v_pk_add_f32 v[62:63], v[62:63], v[76:77]
	v_pk_add_f32 v[74:75], v[66:67], v[68:69]
	v_pk_mul_f32 v[68:69], v[66:67], v[68:69]
	v_pk_add_f32 v[16:17], v[72:73], v[16:17]
	v_pk_fma_f32 v[72:73], v[28:29], v[28:29], v[0:1] op_sel_hi:[1,1,0]
	v_pk_mul_f32 v[64:65], v[24:25], v[24:25]
	v_mov_b32_e32 v75, v69
	v_pk_add_f32 v[68:69], v[22:23], v[62:63]
	v_pk_mul_f32 v[62:63], v[22:23], v[62:63]
	v_mov_b32_e32 v71, v65
	v_mov_b32_e32 v69, v63
	v_mov_b32_e32 v73, v64
	v_mul_f32_e32 v0, v15, v15
	v_pk_add_f32 v[62:63], v[74:75], v[68:69]
	v_pk_add_f32 v[64:65], v[70:71], v[72:73]
	v_pk_fma_f32 v[108:109], v[14:15], v[14:15], v[0:1] op_sel_hi:[1,1,0]
	v_mul_f32_e32 v0, v17, v17
	v_pk_add_f32 v[62:63], v[62:63], v[64:65]
	v_pk_fma_f32 v[114:115], v[16:17], v[16:17], v[0:1] op_sel_hi:[1,1,0]
	v_add_f32_e32 v0, v62, v63
	v_pk_mul_f32 v[62:63], v[18:19], v[18:19]
	v_pk_mul_f32 v[64:65], v[20:21], v[20:21]
	v_mov_b32_e32 v129, v62
	v_mov_b32_e32 v111, v63
	v_mov_b32_e32 v109, v64
	v_mov_b32_e32 v115, v65
	v_pk_add_f32 v[62:63], v[128:129], v[110:111]
	v_pk_add_f32 v[64:65], v[108:109], v[114:115]
	v_lshl_add_u64 v[72:73], s[24:25], 0, v[80:81]
	v_pk_add_f32 v[62:63], v[62:63], v[64:65]
	v_lshl_add_u64 v[70:71], v[88:89], 0, s[14:15]
	v_add_f32_e32 v22, v62, v63
	ds_bpermute_b32 v62, v79, v0
	v_lshl_add_u64 v[68:69], v[90:91], 0, s[10:11]
	s_add_u32 s24, s24, s78
	s_addc_u32 s25, s25, s79
	s_add_u32 s16, s16, s78
	s_waitcnt lgkmcnt(0)
	v_add_f32_e32 v0, v0, v62
	ds_bpermute_b32 v62, v120, v0
	s_addc_u32 s17, s17, s79
	s_cmpk_gt_i32 s0, 0x7fff
	s_waitcnt lgkmcnt(0)
	v_add_f32_e32 v0, v0, v62
	ds_bpermute_b32 v62, v121, v0
	s_waitcnt lgkmcnt(0)
	v_add_f32_e32 v0, v0, v62
	ds_bpermute_b32 v62, v122, v0
	s_waitcnt lgkmcnt(0)
	v_add_f32_e32 v0, v0, v62
	ds_bpermute_b32 v62, v123, v0
	s_waitcnt lgkmcnt(0)
	v_add_f32_e32 v0, v0, v62
	ds_bpermute_b32 v62, v215, v0
	s_waitcnt lgkmcnt(0)
	v_add_f32_e32 v0, v0, v62
	v_fmamk_f32 v0, v0, 0x3a000000, v208
	v_cmp_gt_f32_e32 vcc, s26, v0
	v_mul_f32_e32 v62, 0x4f800000, v0
	s_nop 0
	v_cndmask_b32_e32 v0, v0, v62, vcc
	v_sqrt_f32_e32 v62, v0
	s_nop 0
	v_add_u32_e32 v63, -1, v62
	v_fma_f32 v64, -v63, v62, v0
	v_cmp_ge_f32_e64 s[8:9], 0, v64
	v_add_u32_e32 v64, 1, v62
	s_nop 0
	v_cndmask_b32_e64 v63, v62, v63, s[8:9]
	v_fma_f32 v62, -v64, v62, v0
	v_cmp_lt_f32_e64 s[8:9], 0, v62
	s_nop 1
	v_cndmask_b32_e64 v62, v63, v64, s[8:9]
	v_mul_f32_e32 v63, 0x37800000, v62
	v_cndmask_b32_e32 v62, v62, v63, vcc
	v_cmp_class_f32_e32 vcc, v0, v209
	s_nop 1
	v_cndmask_b32_e32 v0, v62, v0, vcc
	v_div_scale_f32 v62, s[8:9], v0, v0, 1.0
	v_rcp_f32_e32 v63, v62
	s_nop 0
	v_fma_f32 v64, -v62, v63, 1.0
	v_fmac_f32_e32 v63, v64, v63
	v_div_scale_f32 v64, vcc, 1.0, v0, 1.0
	v_mul_f32_e32 v65, v64, v63
	v_fma_f32 v66, -v62, v65, v64
	v_fmac_f32_e32 v65, v66, v63
	v_fma_f32 v62, -v62, v65, v64
	v_div_fmas_f32 v62, v62, v63, v65
	v_div_fixup_f32 v0, v62, v0, 1.0
	ds_bpermute_b32 v62, v79, v22
	s_waitcnt lgkmcnt(0)
	v_add_f32_e32 v22, v22, v62
	ds_bpermute_b32 v62, v120, v22
	s_waitcnt lgkmcnt(0)
	v_add_f32_e32 v22, v22, v62
	ds_bpermute_b32 v62, v121, v22
	s_waitcnt lgkmcnt(0)
	v_add_f32_e32 v22, v22, v62
	ds_bpermute_b32 v62, v122, v22
	s_waitcnt lgkmcnt(0)
	v_add_f32_e32 v22, v22, v62
	ds_bpermute_b32 v62, v123, v22
	s_waitcnt lgkmcnt(0)
	v_add_f32_e32 v22, v22, v62
	ds_bpermute_b32 v62, v215, v22
	s_waitcnt lgkmcnt(0)
	v_add_f32_e32 v22, v22, v62
	v_fmamk_f32 v22, v22, 0x3a000000, v208
	v_cmp_gt_f32_e32 vcc, s26, v22
	v_mul_f32_e32 v62, 0x4f800000, v22
	s_nop 0
	v_cndmask_b32_e32 v22, v22, v62, vcc
	v_sqrt_f32_e32 v62, v22
	s_nop 0
	v_add_u32_e32 v63, -1, v62
	v_fma_f32 v64, -v63, v62, v22
	v_cmp_ge_f32_e64 s[8:9], 0, v64
	v_add_u32_e32 v64, 1, v62
	s_nop 0
	v_cndmask_b32_e64 v63, v62, v63, s[8:9]
	v_fma_f32 v62, -v64, v62, v22
	v_cmp_lt_f32_e64 s[8:9], 0, v62
	s_nop 1
	v_cndmask_b32_e64 v62, v63, v64, s[8:9]
	v_mul_f32_e32 v63, 0x37800000, v62
	v_cndmask_b32_e32 v62, v62, v63, vcc
	v_cmp_class_f32_e32 vcc, v22, v209
	s_nop 1
	v_cndmask_b32_e32 v22, v62, v22, vcc
	v_div_scale_f32 v62, s[8:9], v22, v22, 1.0
	v_rcp_f32_e32 v63, v62
	s_nop 0
	v_fma_f32 v64, -v62, v63, 1.0
	v_fmac_f32_e32 v63, v64, v63
	v_div_scale_f32 v64, vcc, 1.0, v22, 1.0
	v_mul_f32_e32 v65, v64, v63
	v_fma_f32 v66, -v62, v65, v64
	v_fmac_f32_e32 v65, v66, v63
	v_fma_f32 v62, -v62, v65, v64
	v_div_fmas_f32 v62, v62, v63, v65
	v_div_fixup_f32 v66, v62, v22, 1.0
	global_load_dwordx4 v[62:65], v[86:87], off
	s_nop 0
	global_store_dwordx4 v[72:73], v[10:13], off sc1 nt
	global_store_dwordx4 v[70:71], v[6:9], off sc1 nt
	v_mov_b32_e32 v22, v67
	v_pk_mul_f32 v[10:11], v[10:11], v[0:1] op_sel_hi:[1,0]
	v_pk_mul_f32 v[12:13], v[12:13], v[0:1] op_sel_hi:[1,0]
	v_pk_mul_f32 v[6:7], v[6:7], v[66:67] op_sel_hi:[1,0]
	v_pk_mul_f32 v[8:9], v[8:9], v[66:67] op_sel_hi:[1,0]
	s_waitcnt vmcnt(2)
	v_pk_mul_f32 v[10:11], v[10:11], v[62:63]
	v_pk_mul_f32 v[12:13], v[12:13], v[64:65]
	v_pk_mul_f32 v[6:7], v[62:63], v[6:7]
	v_pk_mul_f32 v[8:9], v[64:65], v[8:9]
	v_cvt_pk_bf16_f32 v10, v10, v11
	v_cvt_pk_bf16_f32 v11, v12, v13
	v_cvt_pk_bf16_f32 v6, v6, v7
	v_cvt_pk_bf16_f32 v7, v8, v9
	flat_store_dwordx2 v[100:101], v[10:11]
	flat_store_dwordx2 v[68:69], v[6:7]
	global_load_dwordx4 v[6:9], v[86:87], off offset:1024
	s_nop 0
	global_store_dwordx4 v[72:73], v[30:33], off offset:1024 sc1 nt
	global_store_dwordx4 v[70:71], v[2:5], off offset:1024 sc1 nt
	v_pk_mul_f32 v[10:11], v[30:31], v[0:1] op_sel_hi:[1,0]
	v_pk_mul_f32 v[12:13], v[32:33], v[0:1] op_sel_hi:[1,0]
	v_pk_mul_f32 v[2:3], v[2:3], v[66:67] op_sel_hi:[1,0]
	v_pk_mul_f32 v[4:5], v[4:5], v[66:67] op_sel_hi:[1,0]
	s_waitcnt vmcnt(0)
	v_pk_mul_f32 v[10:11], v[10:11], v[6:7]
	v_pk_mul_f32 v[12:13], v[12:13], v[8:9]
	v_pk_mul_f32 v[2:3], v[6:7], v[2:3]
	v_pk_mul_f32 v[4:5], v[8:9], v[4:5]
	v_cvt_pk_bf16_f32 v10, v10, v11
	v_cvt_pk_bf16_f32 v11, v12, v13
	v_cvt_pk_bf16_f32 v2, v2, v3
	v_cvt_pk_bf16_f32 v3, v4, v5
	flat_store_dwordx2 v[100:101], v[10:11] offset:512
	flat_store_dwordx2 v[68:69], v[2:3] offset:512
	global_load_dwordx4 v[2:5], v[86:87], off offset:2048
	v_pk_mul_f32 v[6:7], v[46:47], v[0:1] op_sel_hi:[1,0]
	v_pk_mul_f32 v[8:9], v[48:49], v[0:1] op_sel_hi:[1,0]
	global_store_dwordx4 v[72:73], v[46:49], off offset:2048 sc1 nt
	global_store_dwordx4 v[70:71], v[50:53], off offset:2048 sc1 nt
	v_pk_mul_f32 v[10:11], v[58:59], v[0:1] op_sel_hi:[1,0]
	v_pk_mul_f32 v[12:13], v[60:61], v[0:1] op_sel_hi:[1,0]
	s_waitcnt vmcnt(0)
	v_pk_mul_f32 v[6:7], v[6:7], v[2:3]
	v_pk_mul_f32 v[8:9], v[8:9], v[4:5]
	v_cvt_pk_bf16_f32 v6, v6, v7
	v_cvt_pk_bf16_f32 v7, v8, v9
	flat_store_dwordx2 v[100:101], v[6:7] offset:1024
	v_pk_mul_f32 v[6:7], v[50:51], v[66:67] op_sel_hi:[1,0]
	v_mov_b32_e32 v8, v103
	v_pk_mul_f32 v[2:3], v[6:7], v[2:3]
	v_pk_mul_f32 v[6:7], v[52:53], v[66:67] op_sel_hi:[1,0]
	v_cvt_pk_bf16_f32 v2, v2, v3
	v_pk_mul_f32 v[4:5], v[6:7], v[4:5]
	v_mov_b32_e32 v6, v104
	v_cvt_pk_bf16_f32 v3, v4, v5
	flat_store_dwordx2 v[68:69], v[2:3] offset:1024
	global_load_dwordx4 v[2:5], v[86:87], off offset:3072
	v_mov_b32_e32 v7, v102
	v_mov_b32_e32 v9, v105
	v_mov_b32_e32 v104, v103
	global_store_dwordx4 v[72:73], v[6:9], off offset:3072 sc1 nt
	global_store_dwordx4 v[70:71], v[54:57], off offset:3072 sc1 nt
	s_nop 0
	v_pk_mul_f32 v[6:7], v[6:7], v[0:1] op_sel_hi:[1,0]
	v_pk_mul_f32 v[8:9], v[104:105], v[0:1] op_sel_hi:[1,0]
	s_waitcnt vmcnt(0)
	v_pk_mul_f32 v[6:7], v[6:7], v[2:3]
	v_pk_mul_f32 v[8:9], v[8:9], v[4:5]
	v_cvt_pk_bf16_f32 v6, v6, v7
	v_cvt_pk_bf16_f32 v7, v8, v9
	flat_store_dwordx2 v[100:101], v[6:7] offset:1536
	v_pk_mul_f32 v[6:7], v[54:55], v[66:67] op_sel_hi:[1,0]
	s_nop 0
	v_pk_mul_f32 v[2:3], v[6:7], v[2:3]
	v_pk_mul_f32 v[6:7], v[56:57], v[66:67] op_sel_hi:[1,0]
	v_cvt_pk_bf16_f32 v2, v2, v3
	v_pk_mul_f32 v[4:5], v[6:7], v[4:5]
	s_nop 0
	v_cvt_pk_bf16_f32 v3, v4, v5
	flat_store_dwordx2 v[68:69], v[2:3] offset:1536
	global_load_dwordx4 v[6:9], v[92:93], off
	v_add_co_u32_e32 v2, vcc, s71, v72
	s_waitcnt vmcnt(0)
	v_pk_mul_f32 v[10:11], v[10:11], v[6:7]
	v_addc_co_u32_e32 v3, vcc, 0, v73, vcc
	v_add_co_u32_e32 v4, vcc, s71, v70
	v_pk_mul_f32 v[12:13], v[12:13], v[8:9]
	s_nop 0
	v_addc_co_u32_e32 v5, vcc, 0, v71, vcc
	v_cvt_pk_bf16_f32 v10, v10, v11
	v_cvt_pk_bf16_f32 v11, v12, v13
	global_store_dwordx4 v[2:3], v[58:61], off sc1 nt
	global_store_dwordx4 v[4:5], v[42:45], off sc1 nt
	flat_store_dwordx2 v[100:101], v[10:11] offset:2048
	v_pk_mul_f32 v[10:11], v[42:43], v[66:67] op_sel_hi:[1,0]
	v_pk_mul_f32 v[12:13], v[40:41], v[0:1] op_sel_hi:[1,0]
	v_pk_mul_f32 v[6:7], v[10:11], v[6:7]
	v_pk_mul_f32 v[10:11], v[44:45], v[66:67] op_sel_hi:[1,0]
	v_cvt_pk_bf16_f32 v6, v6, v7
	v_pk_mul_f32 v[8:9], v[10:11], v[8:9]
	v_pk_mul_f32 v[10:11], v[38:39], v[0:1] op_sel_hi:[1,0]
	v_cvt_pk_bf16_f32 v7, v8, v9
	flat_store_dwordx2 v[68:69], v[6:7] offset:2048
	global_load_dwordx4 v[6:9], v[94:95], off
	s_nop 0
	global_store_dwordx4 v[2:3], v[38:41], off offset:1024 sc1 nt
	global_store_dwordx4 v[4:5], v[34:37], off offset:1024 sc1 nt
	s_waitcnt vmcnt(0)
	v_pk_mul_f32 v[10:11], v[10:11], v[6:7]
	v_pk_mul_f32 v[12:13], v[12:13], v[8:9]
	v_cvt_pk_bf16_f32 v10, v10, v11
	v_cvt_pk_bf16_f32 v11, v12, v13
	flat_store_dwordx2 v[100:101], v[10:11] offset:2560
	v_pk_mul_f32 v[10:11], v[34:35], v[66:67] op_sel_hi:[1,0]
	v_pk_mul_f32 v[12:13], v[28:29], v[0:1] op_sel_hi:[1,0]
	v_pk_mul_f32 v[6:7], v[10:11], v[6:7]
	v_pk_mul_f32 v[10:11], v[36:37], v[66:67] op_sel_hi:[1,0]
	v_cvt_pk_bf16_f32 v6, v6, v7
	v_pk_mul_f32 v[8:9], v[10:11], v[8:9]
	v_pk_mul_f32 v[10:11], v[26:27], v[0:1] op_sel_hi:[1,0]
	v_cvt_pk_bf16_f32 v7, v8, v9
	flat_store_dwordx2 v[68:69], v[6:7] offset:2560
	global_load_dwordx4 v[6:9], v[96:97], off
	s_nop 0
	global_store_dwordx4 v[2:3], v[26:29], off offset:2048 sc1 nt
	global_store_dwordx4 v[4:5], v[14:17], off offset:2048 sc1 nt
	s_waitcnt vmcnt(0)
	v_pk_mul_f32 v[10:11], v[10:11], v[6:7]
	v_pk_mul_f32 v[12:13], v[12:13], v[8:9]
	v_cvt_pk_bf16_f32 v10, v10, v11
	v_cvt_pk_bf16_f32 v11, v12, v13
	flat_store_dwordx2 v[100:101], v[10:11] offset:3072
	v_pk_mul_f32 v[10:11], v[14:15], v[66:67] op_sel_hi:[1,0]
	s_nop 0
	v_pk_mul_f32 v[6:7], v[10:11], v[6:7]
	v_pk_mul_f32 v[10:11], v[16:17], v[66:67] op_sel_hi:[1,0]
	v_cvt_pk_bf16_f32 v6, v6, v7
	v_pk_mul_f32 v[8:9], v[10:11], v[8:9]
	s_nop 0
	v_cvt_pk_bf16_f32 v7, v8, v9
	flat_store_dwordx2 v[68:69], v[6:7] offset:3072
	global_load_dwordx4 v[6:9], v[98:99], off
	s_nop 0
	global_store_dwordx4 v[2:3], v[22:25], off offset:3072 sc1 nt
	global_store_dwordx4 v[4:5], v[18:21], off offset:3072 sc1 nt
	v_pk_mul_f32 v[2:3], v[22:23], v[0:1] op_sel_hi:[1,0]
	v_pk_mul_f32 v[4:5], v[24:25], v[0:1] op_sel_hi:[1,0]
	s_waitcnt vmcnt(0)
	v_pk_mul_f32 v[2:3], v[2:3], v[6:7]
	v_pk_mul_f32 v[4:5], v[4:5], v[8:9]
	v_cvt_pk_bf16_f32 v2, v2, v3
	v_cvt_pk_bf16_f32 v3, v4, v5
	flat_store_dwordx2 v[100:101], v[2:3] offset:3584
	v_pk_mul_f32 v[2:3], v[18:19], v[66:67] op_sel_hi:[1,0]
	v_pk_mul_f32 v[4:5], v[20:21], v[66:67] op_sel_hi:[1,0]
	v_pk_mul_f32 v[2:3], v[2:3], v[6:7]
	v_pk_mul_f32 v[4:5], v[4:5], v[8:9]
	v_cvt_pk_bf16_f32 v2, v2, v3
	v_cvt_pk_bf16_f32 v3, v4, v5
	v_lshl_add_u64 v[100:101], v[100:101], 0, s[60:61]
	flat_store_dwordx2 v[68:69], v[2:3] offset:3584
	s_cbranch_scc0 .LBB0_834

.LBB0_839:
	s_add_i32 s4, s68, s0
	s_ashr_i32 s5, s4, 31
	s_lshl_b64 s[6:7], s[4:5], 12
	v_lshl_add_u64 v[64:65], v[8:9], 0, s[6:7]
	s_lshl_b64 s[4:5], s[4:5], 13
	flat_load_dwordx2 v[66:67], v[20:21] nt
	global_load_dwordx4 v[2:5], v[22:23], off offset:-4096 nt
	flat_load_dwordx2 v[68:69], v[20:21] offset:512 nt
	global_load_dwordx4 v[28:31], v[22:23], off offset:-3072 nt
	flat_load_dwordx2 v[70:71], v[20:21] offset:1024 nt
	global_load_dwordx4 v[32:35], v[22:23], off offset:-2048 nt
	flat_load_dwordx2 v[124:125], v[20:21] offset:1536 nt
	global_load_dwordx4 v[36:39], v[22:23], off offset:-1024 nt
	flat_load_dwordx2 v[126:127], v[20:21] offset:2048 nt
	global_load_dwordx4 v[40:43], v[22:23], off nt
	flat_load_dwordx2 v[128:129], v[20:21] offset:2560 nt
	global_load_dwordx4 v[44:47], v[22:23], off offset:1024 nt
	flat_load_dwordx2 v[130:131], v[20:21] offset:3072 nt
	global_load_dwordx4 v[100:103], v[22:23], off offset:2048 nt
	flat_load_dwordx2 v[132:133], v[20:21] offset:3584 nt
	global_load_dwordx4 v[104:107], v[22:23], off offset:3072 nt
	v_lshl_add_u64 v[26:27], v[6:7], 0, s[4:5]
	flat_load_dwordx2 v[72:73], v[64:65] nt
	global_load_dwordx4 v[48:51], v[26:27], off nt
	flat_load_dwordx2 v[76:77], v[64:65] offset:512 nt
	global_load_dwordx4 v[52:55], v[26:27], off offset:1024 nt
	flat_load_dwordx2 v[134:135], v[64:65] offset:1024 nt
	global_load_dwordx4 v[56:59], v[26:27], off offset:2048 nt
	flat_load_dwordx2 v[136:137], v[64:65] offset:1536 nt
	global_load_dwordx4 v[60:63], v[26:27], off offset:3072 nt
	flat_load_dwordx2 v[138:139], v[64:65] offset:2048 nt
	v_add_co_u32_e32 v24, vcc, s71, v26
	s_add_i32 s0, s0, s58
	s_nop 0
	v_addc_co_u32_e32 v25, vcc, 0, v27, vcc
	global_load_dwordx4 v[108:111], v[24:25], off nt
	flat_load_dwordx2 v[140:141], v[64:65] offset:2560 nt
	global_load_dwordx4 v[112:115], v[24:25], off offset:1024 nt
	flat_load_dwordx2 v[142:143], v[64:65] offset:3072 nt
	global_load_dwordx4 v[116:119], v[24:25], off offset:2048 nt
	flat_load_dwordx2 v[144:145], v[64:65] offset:3584 nt
	global_load_dwordx4 v[120:123], v[24:25], off offset:3072 nt
	v_lshl_add_u64 v[20:21], v[20:21], 0, s[60:61]
	s_cmpk_gt_i32 s0, 0x7fff
	s_waitcnt vmcnt(0) lgkmcnt(0)
	v_lshlrev_b32_e32 v64, 16, v66
	v_and_b32_e32 v65, 0xffff0000, v66
	v_pk_add_f32 v[90:91], v[2:3], v[64:65]
	v_lshlrev_b32_e32 v2, 16, v67
	v_and_b32_e32 v3, 0xffff0000, v67
	v_pk_add_f32 v[92:93], v[4:5], v[2:3]
	v_lshlrev_b32_e32 v2, 16, v72
	v_and_b32_e32 v3, 0xffff0000, v72
	v_pk_add_f32 v[82:83], v[48:49], v[2:3]
	v_lshlrev_b32_e32 v48, 16, v76
	v_and_b32_e32 v49, 0xffff0000, v76
	v_pk_add_f32 v[74:75], v[52:53], v[48:49]
	v_lshlrev_b32_e32 v48, 16, v77
	v_and_b32_e32 v49, 0xffff0000, v77
	v_lshlrev_b32_e32 v2, 16, v73
	v_and_b32_e32 v3, 0xffff0000, v73
	v_pk_add_f32 v[76:77], v[54:55], v[48:49]
	v_lshlrev_b32_e32 v48, 16, v68
	v_and_b32_e32 v49, 0xffff0000, v68
	v_pk_add_f32 v[84:85], v[50:51], v[2:3]
	v_pk_add_f32 v[86:87], v[28:29], v[48:49]
	v_and_b32_e32 v49, 0xffff0000, v69
	v_lshlrev_b32_e32 v48, 16, v69
	v_mov_b32_e32 v50, v83
	v_mov_b32_e32 v51, v75
	v_pk_add_f32 v[88:89], v[30:31], v[48:49]
	v_mov_b32_e32 v48, v82
	v_mov_b32_e32 v49, v74
	v_pk_mul_f32 v[50:51], v[50:51], v[50:51]
	v_mov_b32_e32 v52, v85
	v_mov_b32_e32 v53, v77
	v_pk_fma_f32 v[48:49], v[48:49], v[48:49], v[50:51]
	v_mov_b32_e32 v50, v84
	v_mov_b32_e32 v51, v76
	v_pk_mul_f32 v[52:53], v[52:53], v[52:53]
	v_pk_mul_f32 v[2:3], v[90:91], v[90:91]
	v_pk_fma_f32 v[50:51], v[50:51], v[50:51], v[52:53]
	v_pk_mul_f32 v[4:5], v[92:93], v[92:93]
	v_pk_add_f32 v[48:49], v[48:49], v[50:51]
	v_lshlrev_b32_e32 v50, 16, v70
	v_and_b32_e32 v51, 0xffff0000, v70
	v_pk_add_f32 v[78:79], v[32:33], v[50:51]
	v_lshlrev_b32_e32 v32, 16, v71
	v_and_b32_e32 v33, 0xffff0000, v71
	v_pk_mov_b32 v[2:3], v[2:3], v[78:79] op_sel:[1,0]
	v_mul_f32_e32 v0, v87, v87
	v_pk_add_f32 v[80:81], v[34:35], v[32:33]
	v_lshlrev_b32_e32 v32, 16, v134
	v_and_b32_e32 v33, 0xffff0000, v134
	v_pk_fma_f32 v[34:35], v[90:91], v[90:91], v[2:3]
	v_pk_mul_f32 v[2:3], v[78:79], v[2:3] op_sel_hi:[0,1]
	v_pk_fma_f32 v[28:29], v[86:87], v[86:87], v[0:1] op_sel_hi:[1,1,0]
	v_mul_f32_e32 v0, v89, v89
	v_pk_add_f32 v[66:67], v[56:57], v[32:33]
	v_lshlrev_b32_e32 v32, 16, v135
	v_and_b32_e32 v33, 0xffff0000, v135
	v_mov_b32_e32 v35, v3
	v_mov_b32_e32 v2, v5
	v_mov_b32_e32 v3, v79
	v_pk_fma_f32 v[30:31], v[88:89], v[88:89], v[0:1] op_sel_hi:[1,1,0]
	v_pk_add_f32 v[68:69], v[58:59], v[32:33]
	v_pk_mul_f32 v[32:33], v[80:81], v[80:81]
	v_pk_fma_f32 v[2:3], v[92:93], v[92:93], v[2:3]
	v_pk_mul_f32 v[4:5], v[78:79], v[78:79]
	v_mov_b32_e32 v29, v33
	v_mov_b32_e32 v3, v5
	v_mov_b32_e32 v31, v32
	v_pk_add_f32 v[2:3], v[34:35], v[2:3]
	v_pk_add_f32 v[4:5], v[28:29], v[30:31]
	v_mov_b32_e32 v28, v67
	v_mov_b32_e32 v29, v69
	v_pk_add_f32 v[2:3], v[2:3], v[4:5]
	v_mov_b32_e32 v4, v66
	v_mov_b32_e32 v5, v68
	v_pk_mul_f32 v[28:29], v[28:29], v[28:29]
	v_mov_b32_e32 v30, v37
	v_pk_fma_f32 v[4:5], v[4:5], v[4:5], v[28:29]
	v_lshlrev_b32_e32 v28, 16, v136
	v_and_b32_e32 v29, 0xffff0000, v136
	v_pk_add_f32 v[58:59], v[60:61], v[28:29]
	v_lshlrev_b32_e32 v28, 16, v137
	v_and_b32_e32 v29, 0xffff0000, v137
	v_pk_add_f32 v[60:61], v[62:63], v[28:29]
	v_and_b32_e32 v28, 0xffff0000, v124
	v_lshlrev_b32_e32 v29, 16, v125
	v_mov_b32_e32 v31, v38
	v_lshlrev_b32_e32 v32, 16, v138
	v_and_b32_e32 v33, 0xffff0000, v138
	v_pk_add_f32 v[72:73], v[30:31], v[28:29]
	v_lshlrev_b32_e32 v28, 16, v124
	v_and_b32_e32 v29, 0xffff0000, v125
	v_mov_b32_e32 v37, v39
	v_pk_add_f32 v[50:51], v[108:109], v[32:33]
	v_lshlrev_b32_e32 v32, 16, v139
	v_and_b32_e32 v33, 0xffff0000, v139
	v_pk_add_f32 v[70:71], v[36:37], v[28:29]
	v_pk_mul_f32 v[28:29], v[72:73], v[72:73]
	v_mul_f32_e32 v0, v59, v59
	v_pk_add_f32 v[52:53], v[110:111], v[32:33]
	v_lshlrev_b32_e32 v32, 16, v126
	v_and_b32_e32 v33, 0xffff0000, v126
	v_pk_fma_f32 v[38:39], v[70:71], v[70:71], v[28:29]
	v_pk_fma_f32 v[28:29], v[58:59], v[58:59], v[0:1] op_sel_hi:[1,1,0]
	v_mul_f32_e32 v0, v61, v61
	v_pk_add_f32 v[62:63], v[40:41], v[32:33]
	v_and_b32_e32 v33, 0xffff0000, v127
	v_lshlrev_b32_e32 v32, 16, v127
	v_pk_add_f32 v[48:49], v[48:49], v[48:49] op_sel:[0,1] op_sel_hi:[1,0]
	v_pk_add_f32 v[4:5], v[4:5], v[4:5] op_sel:[0,1] op_sel_hi:[1,0]
	v_pk_fma_f32 v[30:31], v[60:61], v[60:61], v[0:1] op_sel_hi:[1,1,0]
	v_pk_add_f32 v[64:65], v[42:43], v[32:33]
	v_pk_mul_f32 v[32:33], v[50:51], v[50:51]
	v_pk_mul_f32 v[34:35], v[52:53], v[52:53]
	v_mov_b32_e32 v49, v32
	v_mov_b32_e32 v5, v33
	v_mov_b32_e32 v29, v34
	v_mov_b32_e32 v31, v35
	v_pk_add_f32 v[4:5], v[48:49], v[4:5]
	v_pk_add_f32 v[28:29], v[28:29], v[30:31]
	v_mul_f32_e32 v0, v63, v63
	v_pk_add_f32 v[4:5], v[4:5], v[28:29]
	v_lshlrev_b32_e32 v28, 16, v128
	v_and_b32_e32 v29, 0xffff0000, v128
	v_pk_add_f32 v[54:55], v[44:45], v[28:29]
	v_lshlrev_b32_e32 v28, 16, v129
	v_and_b32_e32 v29, 0xffff0000, v129
	v_pk_add_f32 v[56:57], v[46:47], v[28:29]
	v_lshlrev_b32_e32 v28, 16, v140
	v_and_b32_e32 v29, 0xffff0000, v140
	v_pk_add_f32 v[44:45], v[112:113], v[28:29]
	v_lshlrev_b32_e32 v28, 16, v141
	v_and_b32_e32 v29, 0xffff0000, v141
	v_pk_add_f32 v[46:47], v[114:115], v[28:29]
	v_mov_b32_e32 v30, v45
	v_mov_b32_e32 v31, v47
	v_mov_b32_e32 v28, v44
	v_mov_b32_e32 v29, v46
	v_pk_mul_f32 v[30:31], v[30:31], v[30:31]
	v_pk_fma_f32 v[40:41], v[62:63], v[62:63], v[0:1] op_sel_hi:[1,1,0]
	v_pk_fma_f32 v[28:29], v[28:29], v[28:29], v[30:31]
	v_mul_f32_e32 v0, v65, v65
	v_pk_add_f32 v[114:115], v[28:29], v[28:29] op_sel:[0,1] op_sel_hi:[1,0]
	v_lshlrev_b32_e32 v28, 16, v142
	v_and_b32_e32 v29, 0xffff0000, v142
	v_pk_fma_f32 v[108:109], v[64:65], v[64:65], v[0:1] op_sel_hi:[1,1,0]
	v_pk_add_f32 v[30:31], v[116:117], v[28:29]
	v_lshlrev_b32_e32 v28, 16, v143
	v_and_b32_e32 v29, 0xffff0000, v143
	v_pk_add_f32 v[2:3], v[2:3], v[2:3] op_sel:[0,1] op_sel_hi:[1,0]
	v_pk_mul_f32 v[110:111], v[54:55], v[54:55]
	v_pk_add_f32 v[36:37], v[118:119], v[28:29]
	v_lshlrev_b32_e32 v28, 16, v130
	v_and_b32_e32 v29, 0xffff0000, v130
	v_lshlrev_b32_e32 v109, 16, v132
	v_pk_add_f32 v[38:39], v[38:39], v[38:39] op_sel:[0,1] op_sel_hi:[1,0]
	v_pk_mul_f32 v[112:113], v[56:57], v[56:57]
	v_pk_add_f32 v[42:43], v[100:101], v[28:29]
	v_and_b32_e32 v29, 0xffff0000, v131
	v_lshlrev_b32_e32 v28, 16, v131
	v_and_b32_e32 v125, 0xffff0000, v132
	v_mov_b32_e32 v3, v104
	v_mov_b32_e32 v39, v109
	v_mov_b32_e32 v41, v104
	v_mov_b32_e32 v104, v110
	v_mov_b32_e32 v124, v111
	v_mul_f32_e32 v0, v43, v43
	v_pk_add_f32 v[48:49], v[102:103], v[28:29]
	v_lshlrev_b32_e32 v28, 16, v133
	v_and_b32_e32 v29, 0xffff0000, v133
	v_pk_add_f32 v[38:39], v[2:3], v[38:39]
	v_pk_add_f32 v[2:3], v[40:41], v[108:109]
	v_pk_add_f32 v[40:41], v[104:105], v[124:125]
	v_mov_b32_e32 v104, v113
	v_mov_b32_e32 v113, v125
	v_pk_fma_f32 v[100:101], v[42:43], v[42:43], v[0:1] op_sel_hi:[1,1,0]
	v_mul_f32_e32 v0, v49, v49
	v_pk_add_f32 v[32:33], v[106:107], v[28:29]
	v_pk_add_f32 v[104:105], v[104:105], v[112:113]
	v_pk_add_f32 v[108:109], v[38:39], v[2:3]
	v_pk_mul_f32 v[2:3], v[38:39], v[2:3]
	v_pk_fma_f32 v[102:103], v[48:49], v[48:49], v[0:1] op_sel_hi:[1,1,0]
	v_pk_mul_f32 v[106:107], v[32:33], v[32:33]
	v_mov_b32_e32 v109, v3
	v_pk_add_f32 v[2:3], v[40:41], v[104:105]
	v_pk_mul_f32 v[104:105], v[40:41], v[104:105]
	v_mov_b32_e32 v101, v107
	v_mov_b32_e32 v3, v105
	v_mov_b32_e32 v103, v106
	v_mul_f32_e32 v0, v31, v31
	v_lshlrev_b32_e32 v28, 16, v144
	v_and_b32_e32 v29, 0xffff0000, v144
	v_lshlrev_b32_e32 v34, 16, v145
	v_and_b32_e32 v35, 0xffff0000, v145
	v_pk_add_f32 v[2:3], v[108:109], v[2:3]
	v_pk_add_f32 v[100:101], v[100:101], v[102:103]
	v_pk_fma_f32 v[116:117], v[30:31], v[30:31], v[0:1] op_sel_hi:[1,1,0]
	v_mul_f32_e32 v0, v37, v37
	v_pk_add_f32 v[28:29], v[120:121], v[28:29]
	v_pk_add_f32 v[34:35], v[122:123], v[34:35]
	v_pk_add_f32 v[2:3], v[2:3], v[100:101]
	v_pk_add_f32 v[4:5], v[4:5], v[4:5] op_sel:[0,1] op_sel_hi:[1,0]
	v_pk_fma_f32 v[118:119], v[36:37], v[36:37], v[0:1] op_sel_hi:[1,1,0]
	v_add_f32_e32 v0, v2, v3
	v_pk_mul_f32 v[2:3], v[28:29], v[28:29]
	v_pk_mul_f32 v[100:101], v[34:35], v[34:35]
	v_mov_b32_e32 v5, v2
	v_mov_b32_e32 v115, v3
	v_mov_b32_e32 v117, v100
	v_mov_b32_e32 v119, v101
	v_pk_add_f32 v[2:3], v[4:5], v[114:115]
	v_pk_add_f32 v[4:5], v[116:117], v[118:119]
	s_nop 0
	v_pk_add_f32 v[2:3], v[2:3], v[4:5]
	s_nop 0
	v_add_f32_e32 v2, v2, v3
	ds_bpermute_b32 v3, v94, v0
	s_waitcnt lgkmcnt(0)
	v_add_f32_e32 v0, v0, v3
	ds_bpermute_b32 v3, v95, v0
	s_waitcnt lgkmcnt(0)
	v_add_f32_e32 v0, v0, v3
	ds_bpermute_b32 v3, v96, v0
	s_waitcnt lgkmcnt(0)
	v_add_f32_e32 v0, v0, v3
	ds_bpermute_b32 v3, v97, v0
	s_waitcnt lgkmcnt(0)
	v_add_f32_e32 v0, v0, v3
	ds_bpermute_b32 v3, v98, v0
	s_waitcnt lgkmcnt(0)
	v_add_f32_e32 v0, v0, v3
	ds_bpermute_b32 v3, v215, v0
	s_waitcnt lgkmcnt(0)
	v_add_f32_e32 v0, v0, v3
	v_fmamk_f32 v0, v0, 0x3a000000, v208
	v_cmp_gt_f32_e32 vcc, s1, v0
	v_mul_f32_e32 v3, 0x4f800000, v0
	s_nop 0
	v_cndmask_b32_e32 v0, v0, v3, vcc
	v_sqrt_f32_e32 v3, v0
	s_nop 0
	v_add_u32_e32 v4, -1, v3
	v_fma_f32 v5, -v4, v3, v0
	v_cmp_ge_f32_e64 s[6:7], 0, v5
	v_add_u32_e32 v5, 1, v3
	s_nop 0
	v_cndmask_b32_e64 v4, v3, v4, s[6:7]
	v_fma_f32 v3, -v5, v3, v0
	v_cmp_lt_f32_e64 s[6:7], 0, v3
	s_nop 1
	v_cndmask_b32_e64 v3, v4, v5, s[6:7]
	v_mul_f32_e32 v4, 0x37800000, v3
	v_cndmask_b32_e32 v3, v3, v4, vcc
	v_cmp_class_f32_e32 vcc, v0, v209
	s_nop 1
	v_cndmask_b32_e32 v0, v3, v0, vcc
	v_div_scale_f32 v3, s[4:5], v0, v0, 1.0
	v_rcp_f32_e32 v4, v3
	s_nop 0
	v_fma_f32 v5, -v3, v4, 1.0
	v_fmac_f32_e32 v4, v5, v4
	v_div_scale_f32 v5, vcc, 1.0, v0, 1.0
	v_mul_f32_e32 v38, v5, v4
	v_fma_f32 v40, -v3, v38, v5
	v_fmac_f32_e32 v38, v40, v4
	v_fma_f32 v3, -v3, v38, v5
	v_div_fmas_f32 v3, v3, v4, v38
	v_div_fixup_f32 v0, v3, v0, 1.0
	ds_bpermute_b32 v3, v94, v2
	v_pk_mul_f32 v[90:91], v[90:91], v[0:1] op_sel_hi:[1,0]
	v_pk_mul_f32 v[92:93], v[92:93], v[0:1] op_sel_hi:[1,0]
	v_pk_mul_f32 v[42:43], v[42:43], v[0:1] op_sel_hi:[1,0]
	s_waitcnt lgkmcnt(0)
	v_add_f32_e32 v2, v2, v3
	ds_bpermute_b32 v3, v95, v2
	s_waitcnt lgkmcnt(0)
	v_add_f32_e32 v2, v2, v3
	ds_bpermute_b32 v3, v96, v2
	s_waitcnt lgkmcnt(0)
	v_add_f32_e32 v2, v2, v3
	ds_bpermute_b32 v3, v97, v2
	s_waitcnt lgkmcnt(0)
	v_add_f32_e32 v2, v2, v3
	ds_bpermute_b32 v3, v98, v2
	s_waitcnt lgkmcnt(0)
	v_add_f32_e32 v2, v2, v3
	ds_bpermute_b32 v3, v215, v2
	s_waitcnt lgkmcnt(0)
	v_add_f32_e32 v2, v2, v3
	v_fmamk_f32 v2, v2, 0x3a000000, v208
	v_cmp_gt_f32_e32 vcc, s1, v2
	v_mul_f32_e32 v3, 0x4f800000, v2
	s_nop 0
	v_cndmask_b32_e32 v2, v2, v3, vcc
	v_sqrt_f32_e32 v3, v2
	s_nop 0
	v_add_u32_e32 v4, -1, v3
	v_fma_f32 v5, -v4, v3, v2
	v_cmp_ge_f32_e64 s[6:7], 0, v5
	v_add_u32_e32 v5, 1, v3
	s_nop 0
	v_cndmask_b32_e64 v4, v3, v4, s[6:7]
	v_fma_f32 v3, -v5, v3, v2
	v_cmp_lt_f32_e64 s[6:7], 0, v3
	s_nop 1
	v_cndmask_b32_e64 v3, v4, v5, s[6:7]
	v_mul_f32_e32 v4, 0x37800000, v3
	v_cndmask_b32_e32 v3, v3, v4, vcc
	v_cmp_class_f32_e32 vcc, v2, v209
	s_nop 1
	v_cndmask_b32_e32 v2, v3, v2, vcc
	v_div_scale_f32 v3, s[4:5], v2, v2, 1.0
	v_rcp_f32_e32 v4, v3
	s_nop 0
	v_fma_f32 v5, -v3, v4, 1.0
	v_fmac_f32_e32 v4, v5, v4
	v_div_scale_f32 v5, vcc, 1.0, v2, 1.0
	v_mul_f32_e32 v38, v5, v4
	v_fma_f32 v40, -v3, v38, v5
	v_fmac_f32_e32 v38, v40, v4
	v_fma_f32 v3, -v3, v38, v5
	v_div_fmas_f32 v3, v3, v4, v38
	v_div_fixup_f32 v38, v3, v2, 1.0
	global_load_dwordx4 v[2:5], v[10:11], off
	v_pk_mul_f32 v[82:83], v[82:83], v[38:39] op_sel_hi:[1,0]
	v_pk_mul_f32 v[84:85], v[84:85], v[38:39] op_sel_hi:[1,0]
	v_pk_mul_f32 v[76:77], v[76:77], v[38:39] op_sel_hi:[1,0]
	v_pk_mul_f32 v[74:75], v[74:75], v[38:39] op_sel_hi:[1,0]
	v_pk_mul_f32 v[68:69], v[68:69], v[38:39] op_sel_hi:[1,0]
	v_pk_mul_f32 v[66:67], v[66:67], v[38:39] op_sel_hi:[1,0]
	v_pk_mul_f32 v[60:61], v[60:61], v[38:39] op_sel_hi:[1,0]
	v_pk_mul_f32 v[58:59], v[58:59], v[38:39] op_sel_hi:[1,0]
	v_pk_mul_f32 v[50:51], v[50:51], v[38:39] op_sel_hi:[1,0]
	v_pk_mul_f32 v[44:45], v[44:45], v[38:39] op_sel_hi:[1,0]
	v_pk_mul_f32 v[30:31], v[30:31], v[38:39] op_sel_hi:[1,0]
	v_mov_b32_e32 v40, v39
	v_pk_mul_f32 v[28:29], v[28:29], v[38:39] op_sel_hi:[1,0]
	s_waitcnt vmcnt(0)
	v_pk_mul_f32 v[92:93], v[4:5], v[92:93]
	v_pk_mul_f32 v[90:91], v[2:3], v[90:91]
	v_pk_mul_f32 v[4:5], v[4:5], v[84:85]
	v_pk_mul_f32 v[2:3], v[2:3], v[82:83]
	global_store_dwordx4 v[22:23], v[90:93], off offset:-4096 sc1 nt
	global_store_dwordx4 v[26:27], v[2:5], off sc1 nt
	global_load_dwordx4 v[2:5], v[10:11], off offset:1024
	v_pk_mul_f32 v[84:85], v[88:89], v[0:1] op_sel_hi:[1,0]
	v_pk_mul_f32 v[82:83], v[86:87], v[0:1] op_sel_hi:[1,0]
	s_waitcnt vmcnt(0)
	v_pk_mul_f32 v[84:85], v[84:85], v[4:5]
	v_pk_mul_f32 v[82:83], v[82:83], v[2:3]
	v_pk_mul_f32 v[2:3], v[2:3], v[74:75]
	v_pk_mul_f32 v[4:5], v[4:5], v[76:77]
	global_store_dwordx4 v[22:23], v[82:85], off offset:-3072 sc1 nt
	global_store_dwordx4 v[26:27], v[2:5], off offset:1024 sc1 nt
	global_load_dwordx4 v[2:5], v[10:11], off offset:2048
	v_pk_mul_f32 v[76:77], v[80:81], v[0:1] op_sel_hi:[1,0]
	v_pk_mul_f32 v[74:75], v[78:79], v[0:1] op_sel_hi:[1,0]
	s_waitcnt vmcnt(0)
	v_pk_mul_f32 v[76:77], v[76:77], v[4:5]
	v_pk_mul_f32 v[74:75], v[74:75], v[2:3]
	v_pk_mul_f32 v[2:3], v[2:3], v[66:67]
	v_pk_mul_f32 v[4:5], v[4:5], v[68:69]
	global_store_dwordx4 v[22:23], v[74:77], off offset:-2048 sc1 nt
	global_store_dwordx4 v[26:27], v[2:5], off offset:2048 sc1 nt
	global_load_dwordx4 v[2:5], v[10:11], off offset:3072
	v_mov_b32_e32 v66, v73
	v_mov_b32_e32 v67, v71
	v_mov_b32_e32 v71, v72
	v_pk_mul_f32 v[68:69], v[66:67], v[0:1] op_sel_hi:[1,0]
	v_pk_mul_f32 v[66:67], v[70:71], v[0:1] op_sel_hi:[1,0]
	s_waitcnt vmcnt(0)
	v_pk_mul_f32 v[68:69], v[68:69], v[4:5]
	v_pk_mul_f32 v[66:67], v[66:67], v[2:3]
	v_pk_mul_f32 v[2:3], v[58:59], v[2:3]
	v_pk_mul_f32 v[4:5], v[60:61], v[4:5]
	global_store_dwordx4 v[22:23], v[66:69], off offset:-1024 sc1 nt
	global_store_dwordx4 v[26:27], v[2:5], off offset:3072 sc1 nt
	global_load_dwordx4 v[2:5], v[12:13], off
	v_pk_mul_f32 v[26:27], v[64:65], v[0:1] op_sel_hi:[1,0]
	v_pk_mul_f32 v[58:59], v[62:63], v[0:1] op_sel_hi:[1,0]
	s_waitcnt vmcnt(0)
	v_pk_mul_f32 v[60:61], v[26:27], v[4:5]
	v_pk_mul_f32 v[26:27], v[52:53], v[38:39] op_sel_hi:[1,0]
	v_pk_mul_f32 v[58:59], v[58:59], v[2:3]
	v_pk_mul_f32 v[2:3], v[50:51], v[2:3]
	v_pk_mul_f32 v[4:5], v[26:27], v[4:5]
	global_store_dwordx4 v[22:23], v[58:61], off sc1 nt
	global_store_dwordx4 v[24:25], v[2:5], off sc1 nt
	global_load_dwordx4 v[2:5], v[14:15], off
	v_pk_mul_f32 v[26:27], v[56:57], v[0:1] op_sel_hi:[1,0]
	v_pk_mul_f32 v[50:51], v[54:55], v[0:1] op_sel_hi:[1,0]
	s_waitcnt vmcnt(0)
	v_pk_mul_f32 v[52:53], v[26:27], v[4:5]
	v_pk_mul_f32 v[26:27], v[46:47], v[38:39] op_sel_hi:[1,0]
	v_pk_mul_f32 v[50:51], v[50:51], v[2:3]
	v_pk_mul_f32 v[2:3], v[44:45], v[2:3]
	v_pk_mul_f32 v[4:5], v[26:27], v[4:5]
	global_store_dwordx4 v[22:23], v[50:53], off offset:1024 sc1 nt
	global_store_dwordx4 v[24:25], v[2:5], off offset:1024 sc1 nt
	global_load_dwordx4 v[2:5], v[16:17], off
	v_pk_mul_f32 v[26:27], v[48:49], v[0:1] op_sel_hi:[1,0]
	s_waitcnt vmcnt(0)
	v_pk_mul_f32 v[42:43], v[42:43], v[2:3]
	v_pk_mul_f32 v[44:45], v[26:27], v[4:5]
	v_pk_mul_f32 v[26:27], v[36:37], v[38:39] op_sel_hi:[1,0]
	v_pk_mul_f32 v[2:3], v[30:31], v[2:3]
	v_pk_mul_f32 v[4:5], v[26:27], v[4:5]
	global_store_dwordx4 v[22:23], v[42:45], off offset:2048 sc1 nt
	global_store_dwordx4 v[24:25], v[2:5], off offset:2048 sc1 nt
	global_load_dwordx4 v[2:5], v[18:19], off
	v_pk_mul_f32 v[26:27], v[32:33], v[0:1] op_sel_hi:[1,0]
	v_pk_mul_f32 v[30:31], v[40:41], v[0:1] op_sel_hi:[1,0]
	s_waitcnt vmcnt(0)
	v_pk_mul_f32 v[32:33], v[26:27], v[4:5]
	v_pk_mul_f32 v[30:31], v[30:31], v[2:3]
	v_pk_mul_f32 v[26:27], v[34:35], v[38:39] op_sel_hi:[1,0]
	global_store_dwordx4 v[22:23], v[30:33], off offset:3072 sc1 nt
	v_pk_mul_f32 v[2:3], v[28:29], v[2:3]
	v_pk_mul_f32 v[4:5], v[26:27], v[4:5]
	v_lshl_add_u64 v[22:23], v[22:23], 0, s[78:79]
	global_store_dwordx4 v[24:25], v[2:5], off offset:3072 sc1 nt
	s_cbranch_scc0 .LBB0_839
